# attention: K/V operand registers moved to the other VGPR bank residue than Q/P/accumulators
# speedup vs baseline: 1.0116x; 1.0116x over previous
; __device__ __forceinline__ unsigned f2bf(float f) { unsigned u = __builtin_bit_cast(unsigned, f); return (u + 0x7fffu + ((u >> 16) & 1u)) >> 16; }
; __device__ __forceinline__ void attn_item(const bf16_t* __restrict__ Qb, const bf16_t* __restrict__ Kn, const bf16_t* __restrict__ Kr, const bf16_t* __restrict__ Vh,
;                                           const float* __restrict__ csq, bf16_t* __restrict__ Ob, int seq, char* lds) {
;   int tid_ = threadIdx.x; asm volatile("" : "+v"(tid_));
;   const int tid = tid_, wid = tid >> 6, lane = tid & 63, r32 = lane & 31, hi = lane >> 5;
;   bf16_t* V_lds = (bf16_t*)lds; bf16_t* K_lds = (bf16_t*)(lds + 3 * SLOT);
;   float* ws = (float*)(lds + 6 * SLOT) + wid * 64; float* li_l = ws; float* al_l = ws + 32;
;   float mhat = 0.f, l_reg = 0; f32x16 o[2] = {}; bf16x8 qr[6]; f32x16 negm = f32x16{};
;   const bf16_t* Qw = Qb + (long)(wid * QBLK + r32) * 1792 + hi * 8;
; #pragma unroll
;   for (int d0 = 0; d0 < 6; ++d0) qr[d0] = *reinterpret_cast<const bf16x8*>(Qw + d0 * 16);
;   { const float* cp = csq + (long)(wid * QBLK + r32) * 32 + hi * 8;
;     const f32x4 c0 = *(const f32x4*)cp, c1 = *(const f32x4*)(cp + 4), s0 = *(const f32x4*)(cp + 16), s1 = *(const f32x4*)(cp + 20);
;     float cc[8] = {c0[0], c0[1], c0[2], c0[3], c1[0], c1[1], c1[2], c1[3]}, ss[8] = {s0[0], s0[1], s0[2], s0[3], s1[0], s1[1], s1[2], s1[3]};
;     bf16x8 n4, n5;
; #pragma unroll
;     for (int e = 0; e < 8; ++e) { const float x1 = bf2f((unsigned short)qr[4][e]), x2 = bf2f((unsigned short)qr[5][e]);
;       n4[e] = (short)f2bf(x1 * cc[e] - x2 * ss[e]); n5[e] = (short)f2bf(x1 * ss[e] + x2 * cc[e]); }
;     qr[4] = n4; qr[5] = n5; }
;   const int sr = tid >> 3, sc = (tid & 7) * 8, vst0 = v_st(sr, sc);
;   const int rr_ = (tid & 255) >> 2, rc_ = (tid & 3) * 8;
;   const int vb0 = (int)(uintptr_t)V_lds + v_rd_base(lane);
;   struct { bf16x8 vs, kn, kr; } sr_[1];
;     ...
;   f32x16 pA0, pA1, pB0, pB1; float alA, alB; bf16x8 pa0, pa1, pa2, pa3; const int NT = seq / KVBLK;
;   int sp = 0, scu = 0, sn = SLOT;
;     ...
;   if (__builtin_amdgcn_readfirstlane(wid) >= 4) __builtin_amdgcn_s_setprio(1);
;   __syncthreads();
;   SLOAD(0, 0); SWAIT(); SWRITE(0, 0); __syncthreads();
;   qkt(pA0, pA1, K_lds, qr, negm, r32, hi); partialSM<true>(pA0, pA1, mhat, negm, alA);
;   SLOAD(0, KVBLK); SWAIT(); SWRITE(SLOT, 0); __syncthreads();
;   ROT();
.Lat_item:
	s_lshr_b32 s0, s28, 5
	s_and_b32 s1, s28, 31
	s_lshr_b32 s2, s0, 3
	s_and_b32 s0, s0, 7
	s_mul_i32 s10, s2, 0x1c00000
	s_add_u32 s16, s14, 0xd600000
	s_addc_u32 s17, s15, 0
	s_add_u32 s16, s16, s10
	s_addc_u32 s17, s17, 0
	s_mul_i32 s11, s1, 0xe0000
	s_mul_i32 s30, s0, 192
	s_add_i32 s11, s11, s30
	s_add_u32 s16, s16, s11
	s_addc_u32 s17, s17, 0
	s_lshl_b32 s30, s2, 13
	s_lshl_b32 s31, s1, 8
	s_add_i32 s30, s30, s31
	s_lshl_b32 s31, s30, 7
	s_add_u32 s18, s14, 0x5100000
	s_addc_u32 s19, s15, 0
	s_add_u32 s18, s18, s31
	s_addc_u32 s19, s19, 0
	s_lshl_b32 s31, s30, 11
	s_lshl_b32 s11, s0, 7
	s_add_i32 s31, s31, s11
	s_add_u32 s26, s12, s31
	s_addc_u32 s27, s13, 0
	s_lshl_b32 s11, s0, 8
	s_add_i32 s10, s10, s11
	s_add_i32 s10, s10, 0xd600600
	s_lshl_b32 s11, s2, 19
	s_add_i32 s11, s11, 0x1de00000
	v_and_b32_e32 v1, 63, v180
	v_and_b32_e32 v178, 31, v1
	v_lshrrev_b32_e32 v179, 5, v1
	s_lshl_b32 s30, s29, 5
	v_add_u32_e32 v213, s30, v178
	s_movk_i32 s31, 0xe00
	v_mul_lo_u32 v214, v213, s31
	v_lshl_add_u32 v214, v179, 4, v214
	v_lshlrev_b32_e32 v215, 7, v213
	v_lshl_add_u32 v215, v179, 5, v215
	s_barrier
	global_load_dwordx4 v[114:117], v214, s[16:17] offset:0
	global_load_dwordx4 v[118:121], v214, s[16:17] offset:32
	global_load_dwordx4 v[122:125], v214, s[16:17] offset:64
	global_load_dwordx4 v[126:129], v214, s[16:17] offset:96
	global_load_dwordx4 v[130:133], v214, s[16:17] offset:128
	global_load_dwordx4 v[134:137], v214, s[16:17] offset:160
	global_load_dwordx4 v[34:37], v215, s[18:19]
	global_load_dwordx4 v[38:41], v215, s[18:19] offset:16
	global_load_dwordx4 v[42:45], v215, s[18:19] offset:64
	global_load_dwordx4 v[46:49], v215, s[18:19] offset:80
	v_and_b32_e32 v213, 15, v1
	v_lshrrev_b32_e32 v214, 4, v1
	s_lshl_b32 s30, s29, 3
	v_add_u32_e32 v214, s30, v214
	v_add_u32_e32 v215, 0, v214
	v_and_b32_e32 v216, 15, v215
	v_xor_b32_e32 v216, v213, v216
	v_cmp_gt_u32_e32 vcc, 8, v216
	v_and_b32_e32 v217, 7, v216
	v_mov_b32_e32 v177, 64
	v_mov_b32_e32 v1, 0xe00
	v_cndmask_b32_e32 v177, v177, v1, vcc
	v_mul_lo_u32 v177, v215, v177
	v_lshl_add_u32 v177, v217, 4, v177
	v_mov_b32_e32 v1, s11
	v_mov_b32_e32 v217, s10
	v_cndmask_b32_e32 v1, v1, v217, vcc
	v_add_u32_e32 v146, v177, v1
	v_mov_b32_e32 v1, 0x1000
	v_mov_b32_e32 v217, 0x38000
	v_cndmask_b32_e32 v148, v1, v217, vcc
	v_add_u32_e32 v215, 4, v214
	v_and_b32_e32 v216, 15, v215
	v_xor_b32_e32 v216, v213, v216
	v_cmp_gt_u32_e32 vcc, 8, v216
	v_and_b32_e32 v217, 7, v216
	v_mov_b32_e32 v177, 64
	v_mov_b32_e32 v1, 0xe00
	v_cndmask_b32_e32 v177, v177, v1, vcc
	v_mul_lo_u32 v177, v215, v177
	v_lshl_add_u32 v177, v217, 4, v177
	v_mov_b32_e32 v1, s11
	v_mov_b32_e32 v217, s10
	v_cndmask_b32_e32 v1, v1, v217, vcc
	v_add_u32_e32 v147, v177, v1
	v_mov_b32_e32 v1, 0x1000
	v_mov_b32_e32 v217, 0x38000
	v_cndmask_b32_e32 v217, v1, v217, vcc
	v_and_b32_e32 v1, 63, v180
	v_bfe_u32 v213, v1, 2, 3
	v_add_u32_e32 v213, s30, v213
	v_and_b32_e32 v214, 4, v213
	v_and_b32_e32 v215, 8, v213
	v_and_b32_e32 v213, 0xfffffff3, v213
	v_lshl_or_b32 v213, v214, 1, v213
	v_lshrrev_b32_e32 v215, 1, v215
	v_or_b32_e32 v213, v213, v215
	s_movk_i32 s31, 0xe00
	v_mul_lo_u32 v213, v213, s31
	v_and_b32_e32 v214, 3, v1
	v_lshl_add_u32 v213, v214, 4, v213
	v_lshrrev_b32_e32 v214, 5, v1
	v_lshl_add_u32 v213, v214, 6, v213
	s_add_i32 s31, s10, 128
	v_add_u32_e32 v149, s31, v213
	s_add_i32 m0, s6, 0
	s_mov_b64 exec, s[20:21]
	global_load_lds_dwordx4 v146, s[14:15]
	s_add_i32 m0, s6, 1024
	s_mov_b64 exec, s[22:23]
	global_load_lds_dwordx4 v147, s[14:15]
	s_mov_b64 exec, -1
	v_add_u32_e32 v146, v146, v148
	v_add_u32_e32 v147, v147, v217
	s_add_i32 m0, s6, 16384
	s_mov_b64 exec, s[20:21]
	global_load_lds_dwordx4 v146, s[14:15]
	s_add_i32 m0, s6, 17408
	s_mov_b64 exec, s[22:23]
	global_load_lds_dwordx4 v147, s[14:15]
	s_mov_b64 exec, -1
	v_add_u32_e32 v146, v146, v148
	v_add_u32_e32 v147, v147, v217
	s_add_i32 m0, s6, 32768
	s_mov_b64 exec, s[20:21]
	global_load_lds_dwordx4 v146, s[14:15]
	s_add_i32 m0, s6, 33792
	s_mov_b64 exec, s[22:23]
	global_load_lds_dwordx4 v147, s[14:15]
	s_mov_b64 exec, -1
	v_add_u32_e32 v146, v146, v148
	v_add_u32_e32 v147, v147, v217
	s_add_i32 m0, s7, 0
	s_nop 0
	global_load_lds_dwordx4 v149, s[14:15]
	v_add_u32_e32 v149, 0x38000, v149
	s_add_i32 m0, s6, 49152
	s_mov_b64 exec, s[20:21]
	global_load_lds_dwordx4 v146, s[14:15]
	s_add_i32 m0, s6, 50176
	s_mov_b64 exec, s[22:23]
	global_load_lds_dwordx4 v147, s[14:15]
	s_mov_b64 exec, -1
	v_add_u32_e32 v146, v146, v148
	v_add_u32_e32 v147, v147, v217
	s_add_i32 m0, s7, 16384
	s_nop 0
	global_load_lds_dwordx4 v149, s[14:15]
	v_add_u32_e32 v149, 0x38000, v149
	v_mov_b64_e32 v[2:3], 0
	v_mov_b64_e32 v[4:5], 0
	v_mov_b64_e32 v[6:7], 0
	v_mov_b64_e32 v[8:9], 0
	v_mov_b64_e32 v[10:11], 0
	v_mov_b64_e32 v[12:13], 0
	v_mov_b64_e32 v[14:15], 0
	v_mov_b64_e32 v[16:17], 0
	v_mov_b64_e32 v[18:19], 0
	v_mov_b64_e32 v[20:21], 0
	v_mov_b64_e32 v[22:23], 0
	v_mov_b64_e32 v[24:25], 0
	v_mov_b64_e32 v[26:27], 0
	v_mov_b64_e32 v[28:29], 0
	v_mov_b64_e32 v[30:31], 0
	v_mov_b64_e32 v[32:33], 0
	v_mov_b32_e32 v174, 0
	s_waitcnt vmcnt(10)
	v_lshlrev_b32_e32 v66, 16, v130
	v_and_b32_e32 v67, 0xffff0000, v130
	v_lshlrev_b32_e32 v68, 16, v131
	v_and_b32_e32 v69, 0xffff0000, v131
	v_lshlrev_b32_e32 v70, 16, v132
	v_and_b32_e32 v71, 0xffff0000, v132
	v_lshlrev_b32_e32 v72, 16, v133
	v_and_b32_e32 v73, 0xffff0000, v133
	v_lshlrev_b32_e32 v74, 16, v134
	v_and_b32_e32 v75, 0xffff0000, v134
	v_lshlrev_b32_e32 v76, 16, v135
	v_and_b32_e32 v77, 0xffff0000, v135
	v_lshlrev_b32_e32 v78, 16, v136
	v_and_b32_e32 v79, 0xffff0000, v136
	v_lshlrev_b32_e32 v80, 16, v137
	v_and_b32_e32 v81, 0xffff0000, v137
	v_mul_f32_e32 v82, v74, v42
	v_mul_f32_e32 v90, v66, v42
	v_mul_f32_e32 v83, v75, v43
	v_mul_f32_e32 v91, v67, v43
	v_mul_f32_e32 v84, v76, v44
	v_mul_f32_e32 v92, v68, v44
	v_mul_f32_e32 v85, v77, v45
	v_mul_f32_e32 v93, v69, v45
	v_mul_f32_e32 v86, v78, v46
	v_mul_f32_e32 v94, v70, v46
	v_mul_f32_e32 v87, v79, v47
	v_mul_f32_e32 v95, v71, v47
	v_mul_f32_e32 v88, v80, v48
	v_mul_f32_e32 v96, v72, v48
	v_mul_f32_e32 v89, v81, v49
	v_mul_f32_e32 v97, v73, v49
	v_fma_f32 v82, v66, v34, -v82
	v_fma_f32 v90, v74, v34, v90
	v_fma_f32 v83, v67, v35, -v83
	v_fma_f32 v91, v75, v35, v91
	v_fma_f32 v84, v68, v36, -v84
	v_fma_f32 v92, v76, v36, v92
	v_fma_f32 v85, v69, v37, -v85
	v_fma_f32 v93, v77, v37, v93
	v_fma_f32 v86, v70, v38, -v86
	v_fma_f32 v94, v78, v38, v94
	v_fma_f32 v87, v71, v39, -v87
	v_fma_f32 v95, v79, v39, v95
	v_fma_f32 v88, v72, v40, -v88
	v_fma_f32 v96, v80, v40, v96
	v_fma_f32 v89, v73, v41, -v89
	v_fma_f32 v97, v81, v41, v97
	v_cvt_pk_bf16_f32 v130, v82, v83
	v_cvt_pk_bf16_f32 v134, v90, v91
	v_cvt_pk_bf16_f32 v131, v84, v85
	v_cvt_pk_bf16_f32 v135, v92, v93
	v_cvt_pk_bf16_f32 v132, v86, v87
	v_cvt_pk_bf16_f32 v136, v94, v95
	v_cvt_pk_bf16_f32 v133, v88, v89
	v_cvt_pk_bf16_f32 v137, v96, v97
	s_waitcnt vmcnt(8)
	s_barrier
; template <bool FIRST> __device__ __forceinline__ void partialSM(f32x16& p0, f32x16& p1, float& mhat, f32x16& negm, float& alpha) {
;   float pa = fmaxf(fmaxf(p0[0], p0[1]), p1[0]), pb = fmaxf(fmaxf(p0[2], p0[3]), p1[1]); pa = fmaxf(fmaxf(pa, p1[2]), p1[3]);
; #pragma unroll
;   for (int r = 4; r < 16; r += 4) { pa = fmaxf(fmaxf(pa, p0[r]), p0[r + 1]); pb = fmaxf(fmaxf(pb, p0[r + 2]), p0[r + 3]); pa = fmaxf(fmaxf(pa, p1[r]), p1[r + 1]); pb = fmaxf(fmaxf(pb, p1[r + 2]), p1[r + 3]); }
;   float pmax = fmaxf(pa, pb);
;   { auto rr = __builtin_amdgcn_permlane32_swap(__float_as_uint(pmax), __float_as_uint(pmax), false, false);
;     pmax = fmaxf(__uint_as_float(rr[0]), __uint_as_float(rr[1])); }
;   if (!FIRST && __builtin_expect(__all(pmax <= THRL), 1)) { alpha = 1.f; }
;   else { const float d = FIRST ? pmax : fmaxf(pmax, 0.f); mhat += d; alpha = FIRST ? 1.f : __builtin_amdgcn_exp2f(-d);
; #pragma unroll
;     for (int r = 0; r < 16; ++r) { p0[r] -= d; p1[r] -= d; }
; #pragma unroll
;     for (int r = 0; r < 16; ++r) negm[r] = -mhat; }
; #pragma unroll
;   for (int r = 0; r < 16; ++r) p0[r] = __builtin_amdgcn_exp2f(p0[r]);
; }
; __device__ __forceinline__ void finishSM(f32x16& p0, f32x16& p1, float alpha, float& l_reg, bf16x8& pa0, bf16x8& pa1, bf16x8& pa2, bf16x8& pa3) {
; #pragma unroll
;   for (int r = 0; r < 16; ++r) p1[r] = __builtin_amdgcn_exp2f(p1[r]);
;   float ps = 0;
; #pragma unroll
;   for (int r = 0; r < 16; ++r) ps += p0[r];
; #pragma unroll
;   for (int r = 0; r < 16; ++r) ps += p1[r];
;   { auto rr = __builtin_amdgcn_permlane32_swap(__float_as_uint(ps), __float_as_uint(ps), false, false);
;     ps = __uint_as_float(rr[0]) + __uint_as_float(rr[1]); }
;   l_reg = l_reg * alpha + ps;
;     ...
;   PK4(p0, 0, pa0); PK4(p0, 8, pa1); PK4(p1, 0, pa2); PK4(p1, 8, pa3);
;     ...
; }
; __device__ __forceinline__ void qkt(f32x16& p0, f32x16& p1, const bf16_t* Ks, const bf16x8* qr, const f32x16& negm, int r32, int hi) {
;   p0 = negm; p1 = negm;
; #pragma unroll
;   for (int d0 = 0; d0 < 6; ++d0) { int cb = (d0 * 16 + hi * 8) * 2;
;     bf16x8 b0 = *reinterpret_cast<const bf16x8*>((const char*)Ks + KSWZ(r32, cb));
;     bf16x8 b1 = *reinterpret_cast<const bf16x8*>((const char*)Ks + KSWZ(32 + r32, cb));
;     p0 = __builtin_amdgcn_mfma_f32_32x32x16_bf16(b0, qr[d0], p0, 0, 0, 0);
;     p1 = __builtin_amdgcn_mfma_f32_32x32x16_bf16(b1, qr[d0], p1, 0, 0, 0); }
; }
	ds_read_b128 v[184:187], v140 offset:0
	ds_read_b128 v[188:191], v140 offset:8192
	ds_read_b128 v[192:195], v141 offset:0
	ds_read_b128 v[196:199], v141 offset:8192
	ds_read_b128 v[200:203], v142 offset:0
	ds_read_b128 v[204:207], v142 offset:8192
	ds_read_b128 v[208:211], v143 offset:0
	ds_read_b128 v[212:215], v143 offset:8192
	s_waitcnt lgkmcnt(7)
	v_mfma_f32_32x32x16_bf16 v[34:49], v[184:187], v[114:117], 0
	ds_read_b128 v[184:187], v144 offset:0
	s_waitcnt lgkmcnt(7)
	v_mfma_f32_32x32x16_bf16 v[50:65], v[188:191], v[114:117], 0
	ds_read_b128 v[188:191], v144 offset:8192
	s_waitcnt lgkmcnt(7)
	v_mfma_f32_32x32x16_bf16 v[34:49], v[192:195], v[118:121], v[34:49]
	ds_read_b128 v[192:195], v145 offset:0
	s_waitcnt lgkmcnt(7)
	v_mfma_f32_32x32x16_bf16 v[50:65], v[196:199], v[118:121], v[50:65]
	ds_read_b128 v[196:199], v145 offset:8192
	s_waitcnt lgkmcnt(7)
	v_mfma_f32_32x32x16_bf16 v[34:49], v[200:203], v[122:125], v[34:49]
	s_waitcnt lgkmcnt(6)
	v_mfma_f32_32x32x16_bf16 v[50:65], v[204:207], v[122:125], v[50:65]
	s_waitcnt lgkmcnt(5)
	v_mfma_f32_32x32x16_bf16 v[34:49], v[208:211], v[126:129], v[34:49]
	s_waitcnt lgkmcnt(4)
	v_mfma_f32_32x32x16_bf16 v[50:65], v[212:215], v[126:129], v[50:65]
	s_waitcnt lgkmcnt(3)
	v_mfma_f32_32x32x16_bf16 v[34:49], v[184:187], v[130:133], v[34:49]
	s_waitcnt lgkmcnt(2)
	v_mfma_f32_32x32x16_bf16 v[50:65], v[188:191], v[130:133], v[50:65]
	s_waitcnt lgkmcnt(1)
	v_mfma_f32_32x32x16_bf16 v[34:49], v[192:195], v[134:137], v[34:49]
	s_waitcnt lgkmcnt(0)
	v_mfma_f32_32x32x16_bf16 v[50:65], v[196:199], v[134:137], v[50:65]
	s_nop 9
	v_max3_f32 v177, v34, v35, v36
	v_max3_f32 v178, v37, v38, v39
	v_max3_f32 v177, v177, v40, v41
	v_max3_f32 v178, v178, v42, v43
	v_max3_f32 v177, v177, v44, v45
	v_max3_f32 v178, v178, v46, v47
	v_max3_f32 v177, v177, v48, v49
	v_max3_f32 v178, v178, v50, v51
	v_max3_f32 v177, v177, v52, v53
	v_max3_f32 v178, v178, v54, v55
	v_max3_f32 v177, v177, v56, v57
	v_max3_f32 v178, v178, v58, v59
	v_max3_f32 v177, v177, v60, v61
	v_max3_f32 v178, v178, v62, v63
	v_max3_f32 v177, v177, v64, v65
	v_max_f32_e32 v177, v177, v178
	v_mov_b32_e32 v178, v177
	s_nop 1
	v_permlane32_swap_b32_e32 v177, v178
	v_max_f32_e32 v177, v177, v178
	v_mov_b32_e32 v151, v177
	v_sub_f32_e32 v34, v34, v177
	v_sub_f32_e32 v35, v35, v177
	v_sub_f32_e32 v36, v36, v177
	v_sub_f32_e32 v37, v37, v177
	v_sub_f32_e32 v38, v38, v177
	v_sub_f32_e32 v39, v39, v177
	v_sub_f32_e32 v40, v40, v177
	v_sub_f32_e32 v41, v41, v177
	v_sub_f32_e32 v42, v42, v177
	v_sub_f32_e32 v43, v43, v177
	v_sub_f32_e32 v44, v44, v177
	v_sub_f32_e32 v45, v45, v177
	v_sub_f32_e32 v46, v46, v177
	v_sub_f32_e32 v47, v47, v177
	v_sub_f32_e32 v48, v48, v177
	v_sub_f32_e32 v49, v49, v177
	v_sub_f32_e32 v50, v50, v177
	v_sub_f32_e32 v51, v51, v177
	v_sub_f32_e32 v52, v52, v177
	v_sub_f32_e32 v53, v53, v177
	v_sub_f32_e32 v54, v54, v177
	v_sub_f32_e32 v55, v55, v177
	v_sub_f32_e32 v56, v56, v177
	v_sub_f32_e32 v57, v57, v177
	v_sub_f32_e32 v58, v58, v177
	v_sub_f32_e32 v59, v59, v177
	v_sub_f32_e32 v60, v60, v177
	v_sub_f32_e32 v61, v61, v177
	v_sub_f32_e32 v62, v62, v177
	v_sub_f32_e32 v63, v63, v177
	v_sub_f32_e32 v64, v64, v177
	v_sub_f32_e32 v65, v65, v177
	v_xor_b32_e32 v98, 0x80000000, v151
	v_mov_b32_e32 v99, v98
	v_mov_b32_e32 v100, v98
	v_mov_b32_e32 v101, v98
	v_mov_b32_e32 v102, v98
	v_mov_b32_e32 v103, v98
	v_mov_b32_e32 v104, v98
	v_mov_b32_e32 v105, v98
	v_mov_b32_e32 v106, v98
	v_mov_b32_e32 v107, v98
	v_mov_b32_e32 v108, v98
	v_mov_b32_e32 v109, v98
	v_mov_b32_e32 v110, v98
	v_mov_b32_e32 v111, v98
	v_mov_b32_e32 v112, v98
	v_mov_b32_e32 v113, v98
	v_exp_f32_e32 v34, v34
	v_exp_f32_e32 v35, v35
	v_exp_f32_e32 v36, v36
	v_exp_f32_e32 v37, v37
	v_exp_f32_e32 v38, v38
	v_exp_f32_e32 v39, v39
	v_exp_f32_e32 v40, v40
	v_exp_f32_e32 v41, v41
	v_exp_f32_e32 v42, v42
	v_exp_f32_e32 v43, v43
	v_exp_f32_e32 v44, v44
	v_exp_f32_e32 v45, v45
	v_exp_f32_e32 v46, v46
	v_exp_f32_e32 v47, v47
	v_exp_f32_e32 v48, v48
	v_exp_f32_e32 v49, v49
	v_add_f32_e32 v181, v34, v38
	v_add_f32_e32 v182, v35, v39
	v_add_f32_e32 v183, v36, v40
	v_add_f32_e32 v216, v37, v41
	v_add_f32_e32 v181, v181, v42
	v_add_f32_e32 v182, v182, v43
	v_add_f32_e32 v183, v183, v44
	v_add_f32_e32 v216, v216, v45
	v_add_f32_e32 v181, v181, v46
	v_add_f32_e32 v182, v182, v47
	v_add_f32_e32 v183, v183, v48
	v_add_f32_e32 v216, v216, v49
	s_waitcnt vmcnt(3)
	s_barrier
	ds_read_b128 v[184:187], v140 offset:16384
	ds_read_b128 v[188:191], v140 offset:24576
	ds_read_b128 v[192:195], v141 offset:16384
	ds_read_b128 v[196:199], v141 offset:24576
	s_mov_b32 s8, 0
; template <bool FIRST> __device__ __forceinline__ void partialSM(f32x16& p0, f32x16& p1, float& mhat, f32x16& negm, float& alpha) {
;   float pa = fmaxf(fmaxf(p0[0], p0[1]), p1[0]), pb = fmaxf(fmaxf(p0[2], p0[3]), p1[1]); pa = fmaxf(fmaxf(pa, p1[2]), p1[3]);
; #pragma unroll
;   for (int r = 4; r < 16; r += 4) { pa = fmaxf(fmaxf(pa, p0[r]), p0[r + 1]); pb = fmaxf(fmaxf(pb, p0[r + 2]), p0[r + 3]); pa = fmaxf(fmaxf(pa, p1[r]), p1[r + 1]); pb = fmaxf(fmaxf(pb, p1[r + 2]), p1[r + 3]); }
;   float pmax = fmaxf(pa, pb);
;   { auto rr = __builtin_amdgcn_permlane32_swap(__float_as_uint(pmax), __float_as_uint(pmax), false, false);
;     pmax = fmaxf(__uint_as_float(rr[0]), __uint_as_float(rr[1])); }
;   if (!FIRST && __builtin_expect(__all(pmax <= THRL), 1)) { alpha = 1.f; }
;   else { const float d = FIRST ? pmax : fmaxf(pmax, 0.f); mhat += d; alpha = FIRST ? 1.f : __builtin_amdgcn_exp2f(-d);
; #pragma unroll
;     for (int r = 0; r < 16; ++r) { p0[r] -= d; p1[r] -= d; }
; #pragma unroll
;     for (int r = 0; r < 16; ++r) negm[r] = -mhat; }
; #pragma unroll
;   for (int r = 0; r < 16; ++r) p0[r] = __builtin_amdgcn_exp2f(p0[r]);
; }
; __device__ __forceinline__ void finishSM(f32x16& p0, f32x16& p1, float alpha, float& l_reg, bf16x8& pa0, bf16x8& pa1, bf16x8& pa2, bf16x8& pa3) {
; #pragma unroll
;   for (int r = 0; r < 16; ++r) p1[r] = __builtin_amdgcn_exp2f(p1[r]);
;   float ps = 0;
; #pragma unroll
;   for (int r = 0; r < 16; ++r) ps += p0[r];
; #pragma unroll
;   for (int r = 0; r < 16; ++r) ps += p1[r];
;   { auto rr = __builtin_amdgcn_permlane32_swap(__float_as_uint(ps), __float_as_uint(ps), false, false);
;     ps = __uint_as_float(rr[0]) + __uint_as_float(rr[1]); }
;   l_reg = l_reg * alpha + ps;
;     ...
;   PK4(p0, 0, pa0); PK4(p0, 8, pa1); PK4(p1, 0, pa2); PK4(p1, 8, pa3);
;     ...
; }
; __device__ __forceinline__ void qkt(f32x16& p0, f32x16& p1, const bf16_t* Ks, const bf16x8* qr, const f32x16& negm, int r32, int hi) {
;   p0 = negm; p1 = negm;
; #pragma unroll
;   for (int d0 = 0; d0 < 6; ++d0) { int cb = (d0 * 16 + hi * 8) * 2;
;     bf16x8 b0 = *reinterpret_cast<const bf16x8*>((const char*)Ks + KSWZ(r32, cb));
;     bf16x8 b1 = *reinterpret_cast<const bf16x8*>((const char*)Ks + KSWZ(32 + r32, cb));
;     p0 = __builtin_amdgcn_mfma_f32_32x32x16_bf16(b0, qr[d0], p0, 0, 0, 0);
;     p1 = __builtin_amdgcn_mfma_f32_32x32x16_bf16(b1, qr[d0], p1, 0, 0, 0); }
; }
.Lat_loop:
	ds_read_b128 v[200:203], v142 offset:16384
	ds_read_b128 v[204:207], v142 offset:24576
	ds_read_b128 v[208:211], v143 offset:16384
	ds_read_b128 v[212:215], v143 offset:24576
	s_add_i32 m0, s6, 0
	s_mov_b64 exec, s[20:21]
	global_load_lds_dwordx4 v146, s[14:15]
	s_add_i32 m0, s6, 1024
	s_mov_b64 exec, s[22:23]
	global_load_lds_dwordx4 v147, s[14:15]
	s_add_i32 m0, s7, 32768
	s_mov_b64 exec, -1
	global_load_lds_dwordx4 v149, s[14:15]
	v_add_u32_e32 v146, v146, v148
	v_add_u32_e32 v147, v147, v217
	v_add_u32_e32 v149, 0x38000, v149
	s_waitcnt lgkmcnt(6)
	v_mfma_f32_32x32x16_bf16 v[66:81], v[184:187], v[114:117], v[98:113]
	ds_read_b128 v[184:187], v144 offset:16384
	v_exp_f32_e32 v50, v50
	v_exp_f32_e32 v51, v51
	v_exp_f32_e32 v52, v52
	v_exp_f32_e32 v53, v53
	v_exp_f32_e32 v54, v54
	v_mfma_f32_32x32x16_bf16 v[82:97], v[188:191], v[114:117], v[98:113]
	ds_read_b128 v[188:191], v144 offset:24576
	v_exp_f32_e32 v55, v55
	v_exp_f32_e32 v56, v56
	v_exp_f32_e32 v57, v57
	v_exp_f32_e32 v58, v58
	v_exp_f32_e32 v59, v59
	s_waitcnt lgkmcnt(6)
	v_mfma_f32_32x32x16_bf16 v[66:81], v[192:195], v[118:121], v[66:81]
	ds_read_b128 v[192:195], v145 offset:16384
	v_exp_f32_e32 v60, v60
	v_exp_f32_e32 v61, v61
	v_exp_f32_e32 v62, v62
	v_exp_f32_e32 v63, v63
	v_exp_f32_e32 v64, v64
	v_mfma_f32_32x32x16_bf16 v[82:97], v[196:199], v[118:121], v[82:97]
	ds_read_b128 v[196:199], v145 offset:24576
	v_exp_f32_e32 v65, v65
	v_cvt_pk_bf16_f32 v158, v34, v35
	v_cvt_pk_bf16_f32 v159, v36, v37
	v_cvt_pk_bf16_f32 v160, v38, v39
	v_cvt_pk_bf16_f32 v161, v40, v41
	s_waitcnt lgkmcnt(6)
	v_mfma_f32_32x32x16_bf16 v[66:81], v[200:203], v[122:125], v[66:81]
	ds_read_b64_tr_b16 v[200:201], v150 offset:8192
	ds_read_b64_tr_b16 v[202:203], v150 offset:10240
	v_cvt_pk_bf16_f32 v162, v42, v43
	v_cvt_pk_bf16_f32 v163, v44, v45
	v_cvt_pk_bf16_f32 v164, v46, v47
	v_cvt_pk_bf16_f32 v165, v48, v49
	v_permlane32_swap_b32_e32 v158, v160
	v_mfma_f32_32x32x16_bf16 v[82:97], v[204:207], v[122:125], v[82:97]
	ds_read_b64_tr_b16 v[204:205], v150 offset:8704
	ds_read_b64_tr_b16 v[206:207], v150 offset:10752
	v_permlane32_swap_b32_e32 v159, v161
	v_permlane32_swap_b32_e32 v162, v164
	v_permlane32_swap_b32_e32 v163, v165
	v_add_f32_e32 v181, v181, v50
	v_add_f32_e32 v182, v182, v51
	s_waitcnt lgkmcnt(8)
	v_mfma_f32_32x32x16_bf16 v[66:81], v[208:211], v[126:129], v[66:81]
	ds_read_b64_tr_b16 v[208:209], v150 offset:12288
	ds_read_b64_tr_b16 v[210:211], v150 offset:14336
	v_add_f32_e32 v183, v183, v52
	v_add_f32_e32 v216, v216, v53
	v_add_f32_e32 v181, v181, v54
	v_add_f32_e32 v182, v182, v55
	v_add_f32_e32 v183, v183, v56
	v_mfma_f32_32x32x16_bf16 v[82:97], v[212:215], v[126:129], v[82:97]
	ds_read_b64_tr_b16 v[212:213], v150 offset:12800
	ds_read_b64_tr_b16 v[214:215], v150 offset:14848
	v_add_f32_e32 v216, v216, v57
	v_add_f32_e32 v181, v181, v58
	v_add_f32_e32 v182, v182, v59
	v_add_f32_e32 v183, v183, v60
	v_add_f32_e32 v216, v216, v61
	s_waitcnt lgkmcnt(10)
	v_mfma_f32_32x32x16_bf16 v[66:81], v[184:187], v[130:133], v[66:81]
	ds_read_b64_tr_b16 v[184:185], v150 offset:0
	ds_read_b64_tr_b16 v[186:187], v150 offset:2048
	v_add_f32_e32 v181, v181, v62
	v_add_f32_e32 v182, v182, v63
	v_add_f32_e32 v183, v183, v64
	v_add_f32_e32 v216, v216, v65
	v_add_f32_e32 v181, v181, v182
	v_mfma_f32_32x32x16_bf16 v[82:97], v[188:191], v[130:133], v[82:97]
	ds_read_b64_tr_b16 v[188:189], v150 offset:512
	ds_read_b64_tr_b16 v[190:191], v150 offset:2560
	v_add_f32_e32 v183, v183, v216
	v_add_f32_e32 v181, v181, v183
	v_add_f32_e32 v174, v174, v181
	v_cvt_pk_bf16_f32 v166, v50, v51
	v_cvt_pk_bf16_f32 v167, v52, v53
	s_waitcnt lgkmcnt(12)
	v_mfma_f32_32x32x16_bf16 v[66:81], v[192:195], v[134:137], v[66:81]
	ds_read_b64_tr_b16 v[192:193], v150 offset:4096
	ds_read_b64_tr_b16 v[194:195], v150 offset:6144
	v_cvt_pk_bf16_f32 v168, v54, v55
	v_cvt_pk_bf16_f32 v169, v56, v57
	v_cvt_pk_bf16_f32 v170, v58, v59
	v_cvt_pk_bf16_f32 v171, v60, v61
	v_cvt_pk_bf16_f32 v172, v62, v63
	v_mfma_f32_32x32x16_bf16 v[82:97], v[196:199], v[134:137], v[82:97]
	ds_read_b64_tr_b16 v[196:197], v150 offset:4608
	s_waitcnt lgkmcnt(14)
	ds_read_b64_tr_b16 v[198:199], v150 offset:6656
	v_cvt_pk_bf16_f32 v173, v64, v65
	v_permlane32_swap_b32_e32 v166, v168
	v_permlane32_swap_b32_e32 v167, v169
	v_permlane32_swap_b32_e32 v170, v172
	v_permlane32_swap_b32_e32 v171, v173
	s_waitcnt lgkmcnt(4)
	v_mfma_f32_32x32x16_bf16 v[2:17], v[158:161], v[184:187], v[2:17]
	ds_read_b128 v[184:187], v140 offset:32768
	v_max3_f32 v177, v66, v67, v68
	v_max3_f32 v178, v69, v70, v71
	v_max3_f32 v177, v177, v72, v73
	v_mfma_f32_32x32x16_bf16 v[18:33], v[158:161], v[188:191], v[18:33]
	ds_read_b128 v[188:191], v140 offset:40960
	v_max3_f32 v178, v178, v74, v75
	v_max3_f32 v177, v177, v76, v77
	v_max3_f32 v178, v178, v78, v79
	v_max3_f32 v177, v177, v80, v81
	v_max3_f32 v178, v178, v82, v83
	v_max3_f32 v177, v177, v84, v85
	s_waitcnt lgkmcnt(2)
	v_mfma_f32_32x32x16_bf16 v[2:17], v[162:165], v[192:195], v[2:17]
	ds_read_b128 v[192:195], v141 offset:32768
	v_max3_f32 v178, v178, v86, v87
	v_max3_f32 v177, v177, v88, v89
	v_max3_f32 v178, v178, v90, v91
	v_max3_f32 v177, v177, v92, v93
	v_max3_f32 v178, v178, v94, v95
	v_max3_f32 v177, v177, v96, v97
	v_mfma_f32_32x32x16_bf16 v[18:33], v[162:165], v[196:199], v[18:33]
	ds_read_b128 v[196:199], v141 offset:40960
	v_max_f32_e32 v177, v177, v178
	v_mov_b32_e32 v178, v177
	s_nop 1
	v_permlane32_swap_b32_e32 v177, v178
	v_max_f32_e32 v177, v177, v178
	v_cmp_ge_f32_e32 vcc, 0x4138aa3b, v177
	s_cmp_eq_u64 vcc, exec
	s_cbranch_scc0 .Lat_rare1_2
; template <bool FIRST> __device__ __forceinline__ void partialSM(f32x16& p0, f32x16& p1, float& mhat, f32x16& negm, float& alpha) {
;   float pa = fmaxf(fmaxf(p0[0], p0[1]), p1[0]), pb = fmaxf(fmaxf(p0[2], p0[3]), p1[1]); pa = fmaxf(fmaxf(pa, p1[2]), p1[3]);
; #pragma unroll
;   for (int r = 4; r < 16; r += 4) { pa = fmaxf(fmaxf(pa, p0[r]), p0[r + 1]); pb = fmaxf(fmaxf(pb, p0[r + 2]), p0[r + 3]); pa = fmaxf(fmaxf(pa, p1[r]), p1[r + 1]); pb = fmaxf(fmaxf(pb, p1[r + 2]), p1[r + 3]); }
;   float pmax = fmaxf(pa, pb);
;   { auto rr = __builtin_amdgcn_permlane32_swap(__float_as_uint(pmax), __float_as_uint(pmax), false, false);
;     pmax = fmaxf(__uint_as_float(rr[0]), __uint_as_float(rr[1])); }
;   if (!FIRST && __builtin_expect(__all(pmax <= THRL), 1)) { alpha = 1.f; }
;   else { const float d = FIRST ? pmax : fmaxf(pmax, 0.f); mhat += d; alpha = FIRST ? 1.f : __builtin_amdgcn_exp2f(-d);
; #pragma unroll
;     for (int r = 0; r < 16; ++r) { p0[r] -= d; p1[r] -= d; }
; #pragma unroll
;     for (int r = 0; r < 16; ++r) negm[r] = -mhat; }
; #pragma unroll
;   for (int r = 0; r < 16; ++r) p0[r] = __builtin_amdgcn_exp2f(p0[r]);
; }
; __device__ __forceinline__ void finishSM(f32x16& p0, f32x16& p1, float alpha, float& l_reg, bf16x8& pa0, bf16x8& pa1, bf16x8& pa2, bf16x8& pa3) {
; #pragma unroll
;   for (int r = 0; r < 16; ++r) p1[r] = __builtin_amdgcn_exp2f(p1[r]);
;   float ps = 0;
; #pragma unroll
;   for (int r = 0; r < 16; ++r) ps += p0[r];
; #pragma unroll
;   for (int r = 0; r < 16; ++r) ps += p1[r];
;   { auto rr = __builtin_amdgcn_permlane32_swap(__float_as_uint(ps), __float_as_uint(ps), false, false);
;     ps = __uint_as_float(rr[0]) + __uint_as_float(rr[1]); }
;   l_reg = l_reg * alpha + ps;
;     ...
;   PK4(p0, 0, pa0); PK4(p0, 8, pa1); PK4(p1, 0, pa2); PK4(p1, 8, pa3);
;     ...
; }
; __device__ __forceinline__ void qkt(f32x16& p0, f32x16& p1, const bf16_t* Ks, const bf16x8* qr, const f32x16& negm, int r32, int hi) {
;   p0 = negm; p1 = negm;
; #pragma unroll
;   for (int d0 = 0; d0 < 6; ++d0) { int cb = (d0 * 16 + hi * 8) * 2;
;     bf16x8 b0 = *reinterpret_cast<const bf16x8*>((const char*)Ks + KSWZ(r32, cb));
;     bf16x8 b1 = *reinterpret_cast<const bf16x8*>((const char*)Ks + KSWZ(32 + r32, cb));
;     p0 = __builtin_amdgcn_mfma_f32_32x32x16_bf16(b0, qr[d0], p0, 0, 0, 0);
;     p1 = __builtin_amdgcn_mfma_f32_32x32x16_bf16(b1, qr[d0], p1, 0, 0, 0); }
; }
.Lat_ri_1:
	v_mfma_f32_32x32x16_bf16 v[2:17], v[166:169], v[200:203], v[2:17]
	v_exp_f32_e32 v66, v66
	v_exp_f32_e32 v67, v67
	v_exp_f32_e32 v68, v68
	v_exp_f32_e32 v69, v69
	v_exp_f32_e32 v70, v70
	v_exp_f32_e32 v71, v71
	v_exp_f32_e32 v72, v72
	v_mfma_f32_32x32x16_bf16 v[18:33], v[166:169], v[204:207], v[18:33]
	v_exp_f32_e32 v73, v73
	v_exp_f32_e32 v74, v74
	v_exp_f32_e32 v75, v75
	v_exp_f32_e32 v76, v76
	v_exp_f32_e32 v77, v77
	v_exp_f32_e32 v78, v78
	v_exp_f32_e32 v79, v79
	v_mfma_f32_32x32x16_bf16 v[2:17], v[170:173], v[208:211], v[2:17]
	v_exp_f32_e32 v80, v80
	v_exp_f32_e32 v81, v81
	v_add_f32_e32 v181, v66, v70
	v_add_f32_e32 v182, v67, v71
	v_add_f32_e32 v183, v68, v72
	v_add_f32_e32 v216, v69, v73
	v_add_f32_e32 v181, v181, v74
	v_mfma_f32_32x32x16_bf16 v[18:33], v[170:173], v[212:215], v[18:33]
	v_add_f32_e32 v182, v182, v75
	v_add_f32_e32 v183, v183, v76
	v_add_f32_e32 v216, v216, v77
	v_add_f32_e32 v181, v181, v78
	v_add_f32_e32 v182, v182, v79
	v_add_f32_e32 v183, v183, v80
	v_add_f32_e32 v216, v216, v81
	s_waitcnt vmcnt(3)
	s_cmp_lg_u32 s9, 0
	s_cbranch_scc1 .Lat_rare2_3
.Lat_rr_4:
	s_waitcnt lgkmcnt(0)
	s_barrier
	ds_read_b128 v[200:203], v142 offset:32768
	ds_read_b128 v[204:207], v142 offset:40960
	ds_read_b128 v[208:211], v143 offset:32768
	ds_read_b128 v[212:215], v143 offset:40960
	s_add_i32 m0, s6, 16384
	s_mov_b64 exec, s[20:21]
	global_load_lds_dwordx4 v146, s[14:15]
	s_add_i32 m0, s6, 17408
	s_mov_b64 exec, s[22:23]
	global_load_lds_dwordx4 v147, s[14:15]
	s_add_i32 m0, s7, 49152
	s_mov_b64 exec, -1
	global_load_lds_dwordx4 v149, s[14:15]
	v_add_u32_e32 v146, v146, v148
	v_add_u32_e32 v147, v147, v217
	v_add_u32_e32 v149, 0x38000, v149
	v_mfma_f32_32x32x16_bf16 v[34:49], v[184:187], v[114:117], v[98:113]
	ds_read_b128 v[184:187], v144 offset:32768
	v_exp_f32_e32 v82, v82
	v_exp_f32_e32 v83, v83
	v_exp_f32_e32 v84, v84
	v_exp_f32_e32 v85, v85
	v_exp_f32_e32 v86, v86
	v_mfma_f32_32x32x16_bf16 v[50:65], v[188:191], v[114:117], v[98:113]
	ds_read_b128 v[188:191], v144 offset:40960
	v_exp_f32_e32 v87, v87
	v_exp_f32_e32 v88, v88
	v_exp_f32_e32 v89, v89
	v_exp_f32_e32 v90, v90
	v_exp_f32_e32 v91, v91
	v_mfma_f32_32x32x16_bf16 v[34:49], v[192:195], v[118:121], v[34:49]
	ds_read_b128 v[192:195], v145 offset:32768
	v_exp_f32_e32 v92, v92
	v_exp_f32_e32 v93, v93
	v_exp_f32_e32 v94, v94
	v_exp_f32_e32 v95, v95
	v_exp_f32_e32 v96, v96
	v_mfma_f32_32x32x16_bf16 v[50:65], v[196:199], v[118:121], v[50:65]
	ds_read_b128 v[196:199], v145 offset:40960
	v_exp_f32_e32 v97, v97
	v_cvt_pk_bf16_f32 v158, v66, v67
	v_cvt_pk_bf16_f32 v159, v68, v69
	v_cvt_pk_bf16_f32 v160, v70, v71
	v_cvt_pk_bf16_f32 v161, v72, v73
	s_waitcnt lgkmcnt(6)
	v_mfma_f32_32x32x16_bf16 v[34:49], v[200:203], v[122:125], v[34:49]
	ds_read_b64_tr_b16 v[200:201], v150 offset:24576
	ds_read_b64_tr_b16 v[202:203], v150 offset:26624
	v_cvt_pk_bf16_f32 v162, v74, v75
	v_cvt_pk_bf16_f32 v163, v76, v77
	v_cvt_pk_bf16_f32 v164, v78, v79
	v_cvt_pk_bf16_f32 v165, v80, v81
	v_permlane32_swap_b32_e32 v158, v160
	v_mfma_f32_32x32x16_bf16 v[50:65], v[204:207], v[122:125], v[50:65]
	ds_read_b64_tr_b16 v[204:205], v150 offset:25088
	ds_read_b64_tr_b16 v[206:207], v150 offset:27136
	v_permlane32_swap_b32_e32 v159, v161
	v_permlane32_swap_b32_e32 v162, v164
	v_permlane32_swap_b32_e32 v163, v165
	v_add_f32_e32 v181, v181, v82
	v_add_f32_e32 v182, v182, v83
	s_waitcnt lgkmcnt(8)
	v_mfma_f32_32x32x16_bf16 v[34:49], v[208:211], v[126:129], v[34:49]
	ds_read_b64_tr_b16 v[208:209], v150 offset:28672
	ds_read_b64_tr_b16 v[210:211], v150 offset:30720
	v_add_f32_e32 v183, v183, v84
	v_add_f32_e32 v216, v216, v85
	v_add_f32_e32 v181, v181, v86
	v_add_f32_e32 v182, v182, v87
	v_add_f32_e32 v183, v183, v88
	v_mfma_f32_32x32x16_bf16 v[50:65], v[212:215], v[126:129], v[50:65]
	ds_read_b64_tr_b16 v[212:213], v150 offset:29184
	ds_read_b64_tr_b16 v[214:215], v150 offset:31232
	v_add_f32_e32 v216, v216, v89
	v_add_f32_e32 v181, v181, v90
	v_add_f32_e32 v182, v182, v91
	v_add_f32_e32 v183, v183, v92
	v_add_f32_e32 v216, v216, v93
	s_waitcnt lgkmcnt(10)
	v_mfma_f32_32x32x16_bf16 v[34:49], v[184:187], v[130:133], v[34:49]
	ds_read_b64_tr_b16 v[184:185], v150 offset:16384
	ds_read_b64_tr_b16 v[186:187], v150 offset:18432
	v_add_f32_e32 v181, v181, v94
	v_add_f32_e32 v182, v182, v95
	v_add_f32_e32 v183, v183, v96
	v_add_f32_e32 v216, v216, v97
	v_add_f32_e32 v181, v181, v182
	v_mfma_f32_32x32x16_bf16 v[50:65], v[188:191], v[130:133], v[50:65]
	ds_read_b64_tr_b16 v[188:189], v150 offset:16896
	ds_read_b64_tr_b16 v[190:191], v150 offset:18944
	v_add_f32_e32 v183, v183, v216
	v_add_f32_e32 v181, v181, v183
	v_add_f32_e32 v174, v174, v181
	v_cvt_pk_bf16_f32 v166, v82, v83
	v_cvt_pk_bf16_f32 v167, v84, v85
	s_waitcnt lgkmcnt(12)
	v_mfma_f32_32x32x16_bf16 v[34:49], v[192:195], v[134:137], v[34:49]
	ds_read_b64_tr_b16 v[192:193], v150 offset:20480
	ds_read_b64_tr_b16 v[194:195], v150 offset:22528
	v_cvt_pk_bf16_f32 v168, v86, v87
	v_cvt_pk_bf16_f32 v169, v88, v89
	v_cvt_pk_bf16_f32 v170, v90, v91
	v_cvt_pk_bf16_f32 v171, v92, v93
	v_cvt_pk_bf16_f32 v172, v94, v95
	v_mfma_f32_32x32x16_bf16 v[50:65], v[196:199], v[134:137], v[50:65]
	ds_read_b64_tr_b16 v[196:197], v150 offset:20992
	s_waitcnt lgkmcnt(14)
	ds_read_b64_tr_b16 v[198:199], v150 offset:23040
	v_cvt_pk_bf16_f32 v173, v96, v97
	v_permlane32_swap_b32_e32 v166, v168
	v_permlane32_swap_b32_e32 v167, v169
	v_permlane32_swap_b32_e32 v170, v172
	v_permlane32_swap_b32_e32 v171, v173
	s_waitcnt lgkmcnt(4)
	v_mfma_f32_32x32x16_bf16 v[2:17], v[158:161], v[184:187], v[2:17]
	ds_read_b128 v[184:187], v140 offset:49152
	v_max3_f32 v177, v34, v35, v36
	v_max3_f32 v178, v37, v38, v39
	v_max3_f32 v177, v177, v40, v41
	v_mfma_f32_32x32x16_bf16 v[18:33], v[158:161], v[188:191], v[18:33]
	ds_read_b128 v[188:191], v140 offset:57344
	v_max3_f32 v178, v178, v42, v43
	v_max3_f32 v177, v177, v44, v45
	v_max3_f32 v178, v178, v46, v47
	v_max3_f32 v177, v177, v48, v49
	v_max3_f32 v178, v178, v50, v51
	v_max3_f32 v177, v177, v52, v53
	s_waitcnt lgkmcnt(2)
	v_mfma_f32_32x32x16_bf16 v[2:17], v[162:165], v[192:195], v[2:17]
	ds_read_b128 v[192:195], v141 offset:49152
	v_max3_f32 v178, v178, v54, v55
	v_max3_f32 v177, v177, v56, v57
	v_max3_f32 v178, v178, v58, v59
	v_max3_f32 v177, v177, v60, v61
	v_max3_f32 v178, v178, v62, v63
	v_max3_f32 v177, v177, v64, v65
	v_mfma_f32_32x32x16_bf16 v[18:33], v[162:165], v[196:199], v[18:33]
	ds_read_b128 v[196:199], v141 offset:57344
	v_max_f32_e32 v177, v177, v178
	v_mov_b32_e32 v178, v177
	s_nop 1
	v_permlane32_swap_b32_e32 v177, v178
	v_max_f32_e32 v177, v177, v178
	v_cmp_ge_f32_e32 vcc, 0x4138aa3b, v177
	s_cmp_eq_u64 vcc, exec
	s_cbranch_scc0 .Lat_rare1_6
; template <bool FIRST> __device__ __forceinline__ void partialSM(f32x16& p0, f32x16& p1, float& mhat, f32x16& negm, float& alpha) {
;   float pa = fmaxf(fmaxf(p0[0], p0[1]), p1[0]), pb = fmaxf(fmaxf(p0[2], p0[3]), p1[1]); pa = fmaxf(fmaxf(pa, p1[2]), p1[3]);
; #pragma unroll
;   for (int r = 4; r < 16; r += 4) { pa = fmaxf(fmaxf(pa, p0[r]), p0[r + 1]); pb = fmaxf(fmaxf(pb, p0[r + 2]), p0[r + 3]); pa = fmaxf(fmaxf(pa, p1[r]), p1[r + 1]); pb = fmaxf(fmaxf(pb, p1[r + 2]), p1[r + 3]); }
;   float pmax = fmaxf(pa, pb);
;   { auto rr = __builtin_amdgcn_permlane32_swap(__float_as_uint(pmax), __float_as_uint(pmax), false, false);
;     pmax = fmaxf(__uint_as_float(rr[0]), __uint_as_float(rr[1])); }
;   if (!FIRST && __builtin_expect(__all(pmax <= THRL), 1)) { alpha = 1.f; }
;   else { const float d = FIRST ? pmax : fmaxf(pmax, 0.f); mhat += d; alpha = FIRST ? 1.f : __builtin_amdgcn_exp2f(-d);
; #pragma unroll
;     for (int r = 0; r < 16; ++r) { p0[r] -= d; p1[r] -= d; }
; #pragma unroll
;     for (int r = 0; r < 16; ++r) negm[r] = -mhat; }
; #pragma unroll
;   for (int r = 0; r < 16; ++r) p0[r] = __builtin_amdgcn_exp2f(p0[r]);
; }
; __device__ __forceinline__ void finishSM(f32x16& p0, f32x16& p1, float alpha, float& l_reg, bf16x8& pa0, bf16x8& pa1, bf16x8& pa2, bf16x8& pa3) {
; #pragma unroll
;   for (int r = 0; r < 16; ++r) p1[r] = __builtin_amdgcn_exp2f(p1[r]);
;   float ps = 0;
; #pragma unroll
;   for (int r = 0; r < 16; ++r) ps += p0[r];
; #pragma unroll
;   for (int r = 0; r < 16; ++r) ps += p1[r];
;   { auto rr = __builtin_amdgcn_permlane32_swap(__float_as_uint(ps), __float_as_uint(ps), false, false);
;     ps = __uint_as_float(rr[0]) + __uint_as_float(rr[1]); }
;   l_reg = l_reg * alpha + ps;
;     ...
;   PK4(p0, 0, pa0); PK4(p0, 8, pa1); PK4(p1, 0, pa2); PK4(p1, 8, pa3);
;     ...
; }
; __device__ __forceinline__ void qkt(f32x16& p0, f32x16& p1, const bf16_t* Ks, const bf16x8* qr, const f32x16& negm, int r32, int hi) {
;   p0 = negm; p1 = negm;
; #pragma unroll
;   for (int d0 = 0; d0 < 6; ++d0) { int cb = (d0 * 16 + hi * 8) * 2;
;     bf16x8 b0 = *reinterpret_cast<const bf16x8*>((const char*)Ks + KSWZ(r32, cb));
;     bf16x8 b1 = *reinterpret_cast<const bf16x8*>((const char*)Ks + KSWZ(32 + r32, cb));
;     p0 = __builtin_amdgcn_mfma_f32_32x32x16_bf16(b0, qr[d0], p0, 0, 0, 0);
;     p1 = __builtin_amdgcn_mfma_f32_32x32x16_bf16(b1, qr[d0], p1, 0, 0, 0); }
; }
.Lat_ri_5:
	v_mfma_f32_32x32x16_bf16 v[2:17], v[166:169], v[200:203], v[2:17]
	v_exp_f32_e32 v34, v34
	v_exp_f32_e32 v35, v35
	v_exp_f32_e32 v36, v36
	v_exp_f32_e32 v37, v37
	v_exp_f32_e32 v38, v38
	v_exp_f32_e32 v39, v39
	v_exp_f32_e32 v40, v40
	v_mfma_f32_32x32x16_bf16 v[18:33], v[166:169], v[204:207], v[18:33]
	v_exp_f32_e32 v41, v41
	v_exp_f32_e32 v42, v42
	v_exp_f32_e32 v43, v43
	v_exp_f32_e32 v44, v44
	v_exp_f32_e32 v45, v45
	v_exp_f32_e32 v46, v46
	v_exp_f32_e32 v47, v47
	v_mfma_f32_32x32x16_bf16 v[2:17], v[170:173], v[208:211], v[2:17]
	v_exp_f32_e32 v48, v48
	v_exp_f32_e32 v49, v49
	v_add_f32_e32 v181, v34, v38
	v_add_f32_e32 v182, v35, v39
	v_add_f32_e32 v183, v36, v40
	v_add_f32_e32 v216, v37, v41
	v_add_f32_e32 v181, v181, v42
	v_mfma_f32_32x32x16_bf16 v[18:33], v[170:173], v[212:215], v[18:33]
	v_add_f32_e32 v182, v182, v43
	v_add_f32_e32 v183, v183, v44
	v_add_f32_e32 v216, v216, v45
	v_add_f32_e32 v181, v181, v46
	v_add_f32_e32 v182, v182, v47
	v_add_f32_e32 v183, v183, v48
	v_add_f32_e32 v216, v216, v49
	s_waitcnt vmcnt(3)
	s_cmp_lg_u32 s9, 0
	s_cbranch_scc1 .Lat_rare2_7
.Lat_rr_8:
	s_waitcnt lgkmcnt(0)
	s_barrier
	ds_read_b128 v[200:203], v142 offset:49152
	ds_read_b128 v[204:207], v142 offset:57344
	ds_read_b128 v[208:211], v143 offset:49152
	ds_read_b128 v[212:215], v143 offset:57344
	s_add_i32 m0, s6, 32768
	s_mov_b64 exec, s[20:21]
	global_load_lds_dwordx4 v146, s[14:15]
	s_add_i32 m0, s6, 33792
	s_mov_b64 exec, s[22:23]
	global_load_lds_dwordx4 v147, s[14:15]
	s_add_i32 m0, s7, 0
	s_mov_b64 exec, -1
	global_load_lds_dwordx4 v149, s[14:15]
	v_add_u32_e32 v146, v146, v148
	v_add_u32_e32 v147, v147, v217
	v_add_u32_e32 v149, 0x38000, v149
	v_mfma_f32_32x32x16_bf16 v[66:81], v[184:187], v[114:117], v[98:113]
	ds_read_b128 v[184:187], v144 offset:49152
	v_exp_f32_e32 v50, v50
	v_exp_f32_e32 v51, v51
	v_exp_f32_e32 v52, v52
	v_exp_f32_e32 v53, v53
	v_exp_f32_e32 v54, v54
	v_mfma_f32_32x32x16_bf16 v[82:97], v[188:191], v[114:117], v[98:113]
	ds_read_b128 v[188:191], v144 offset:57344
	v_exp_f32_e32 v55, v55
	v_exp_f32_e32 v56, v56
	v_exp_f32_e32 v57, v57
	v_exp_f32_e32 v58, v58
	v_exp_f32_e32 v59, v59
	v_mfma_f32_32x32x16_bf16 v[66:81], v[192:195], v[118:121], v[66:81]
	ds_read_b128 v[192:195], v145 offset:49152
	v_exp_f32_e32 v60, v60
	v_exp_f32_e32 v61, v61
	v_exp_f32_e32 v62, v62
	v_exp_f32_e32 v63, v63
	v_exp_f32_e32 v64, v64
	v_mfma_f32_32x32x16_bf16 v[82:97], v[196:199], v[118:121], v[82:97]
	ds_read_b128 v[196:199], v145 offset:57344
	v_exp_f32_e32 v65, v65
	v_cvt_pk_bf16_f32 v158, v34, v35
	v_cvt_pk_bf16_f32 v159, v36, v37
	v_cvt_pk_bf16_f32 v160, v38, v39
	v_cvt_pk_bf16_f32 v161, v40, v41
	s_waitcnt lgkmcnt(6)
	v_mfma_f32_32x32x16_bf16 v[66:81], v[200:203], v[122:125], v[66:81]
	ds_read_b64_tr_b16 v[200:201], v150 offset:40960
	ds_read_b64_tr_b16 v[202:203], v150 offset:43008
	v_cvt_pk_bf16_f32 v162, v42, v43
	v_cvt_pk_bf16_f32 v163, v44, v45
	v_cvt_pk_bf16_f32 v164, v46, v47
	v_cvt_pk_bf16_f32 v165, v48, v49
	v_permlane32_swap_b32_e32 v158, v160
	v_mfma_f32_32x32x16_bf16 v[82:97], v[204:207], v[122:125], v[82:97]
	ds_read_b64_tr_b16 v[204:205], v150 offset:41472
	ds_read_b64_tr_b16 v[206:207], v150 offset:43520
	v_permlane32_swap_b32_e32 v159, v161
	v_permlane32_swap_b32_e32 v162, v164
	v_permlane32_swap_b32_e32 v163, v165
	v_add_f32_e32 v181, v181, v50
	v_add_f32_e32 v182, v182, v51
	s_waitcnt lgkmcnt(8)
	v_mfma_f32_32x32x16_bf16 v[66:81], v[208:211], v[126:129], v[66:81]
	ds_read_b64_tr_b16 v[208:209], v150 offset:45056
	ds_read_b64_tr_b16 v[210:211], v150 offset:47104
	v_add_f32_e32 v183, v183, v52
	v_add_f32_e32 v216, v216, v53
	v_add_f32_e32 v181, v181, v54
	v_add_f32_e32 v182, v182, v55
	v_add_f32_e32 v183, v183, v56
	v_mfma_f32_32x32x16_bf16 v[82:97], v[212:215], v[126:129], v[82:97]
	ds_read_b64_tr_b16 v[212:213], v150 offset:45568
	ds_read_b64_tr_b16 v[214:215], v150 offset:47616
	v_add_f32_e32 v216, v216, v57
	v_add_f32_e32 v181, v181, v58
	v_add_f32_e32 v182, v182, v59
	v_add_f32_e32 v183, v183, v60
	v_add_f32_e32 v216, v216, v61
	s_waitcnt lgkmcnt(10)
	v_mfma_f32_32x32x16_bf16 v[66:81], v[184:187], v[130:133], v[66:81]
	ds_read_b64_tr_b16 v[184:185], v150 offset:32768
	ds_read_b64_tr_b16 v[186:187], v150 offset:34816
	v_add_f32_e32 v181, v181, v62
	v_add_f32_e32 v182, v182, v63
	v_add_f32_e32 v183, v183, v64
	v_add_f32_e32 v216, v216, v65
	v_add_f32_e32 v181, v181, v182
	v_mfma_f32_32x32x16_bf16 v[82:97], v[188:191], v[130:133], v[82:97]
	ds_read_b64_tr_b16 v[188:189], v150 offset:33280
	ds_read_b64_tr_b16 v[190:191], v150 offset:35328
	v_add_f32_e32 v183, v183, v216
	v_add_f32_e32 v181, v181, v183
	v_add_f32_e32 v174, v174, v181
	v_cvt_pk_bf16_f32 v166, v50, v51
	v_cvt_pk_bf16_f32 v167, v52, v53
	s_waitcnt lgkmcnt(12)
	v_mfma_f32_32x32x16_bf16 v[66:81], v[192:195], v[134:137], v[66:81]
	ds_read_b64_tr_b16 v[192:193], v150 offset:36864
	ds_read_b64_tr_b16 v[194:195], v150 offset:38912
	v_cvt_pk_bf16_f32 v168, v54, v55
	v_cvt_pk_bf16_f32 v169, v56, v57
	v_cvt_pk_bf16_f32 v170, v58, v59
	v_cvt_pk_bf16_f32 v171, v60, v61
	v_cvt_pk_bf16_f32 v172, v62, v63
	v_mfma_f32_32x32x16_bf16 v[82:97], v[196:199], v[134:137], v[82:97]
	ds_read_b64_tr_b16 v[196:197], v150 offset:37376
	s_waitcnt lgkmcnt(14)
	ds_read_b64_tr_b16 v[198:199], v150 offset:39424
	v_cvt_pk_bf16_f32 v173, v64, v65
	v_permlane32_swap_b32_e32 v166, v168
	v_permlane32_swap_b32_e32 v167, v169
	v_permlane32_swap_b32_e32 v170, v172
	v_permlane32_swap_b32_e32 v171, v173
	s_waitcnt lgkmcnt(4)
	v_mfma_f32_32x32x16_bf16 v[2:17], v[158:161], v[184:187], v[2:17]
	ds_read_b128 v[184:187], v140 offset:0
	v_max3_f32 v177, v66, v67, v68
	v_max3_f32 v178, v69, v70, v71
	v_max3_f32 v177, v177, v72, v73
	v_mfma_f32_32x32x16_bf16 v[18:33], v[158:161], v[188:191], v[18:33]
	ds_read_b128 v[188:191], v140 offset:8192
	v_max3_f32 v178, v178, v74, v75
	v_max3_f32 v177, v177, v76, v77
	v_max3_f32 v178, v178, v78, v79
	v_max3_f32 v177, v177, v80, v81
	v_max3_f32 v178, v178, v82, v83
	v_max3_f32 v177, v177, v84, v85
	s_waitcnt lgkmcnt(2)
	v_mfma_f32_32x32x16_bf16 v[2:17], v[162:165], v[192:195], v[2:17]
	ds_read_b128 v[192:195], v141 offset:0
	v_max3_f32 v178, v178, v86, v87
	v_max3_f32 v177, v177, v88, v89
	v_max3_f32 v178, v178, v90, v91
	v_max3_f32 v177, v177, v92, v93
	v_max3_f32 v178, v178, v94, v95
	v_max3_f32 v177, v177, v96, v97
	v_mfma_f32_32x32x16_bf16 v[18:33], v[162:165], v[196:199], v[18:33]
	ds_read_b128 v[196:199], v141 offset:8192
	v_max_f32_e32 v177, v177, v178
	v_mov_b32_e32 v178, v177
	s_nop 1
	v_permlane32_swap_b32_e32 v177, v178
	v_max_f32_e32 v177, v177, v178
	v_cmp_ge_f32_e32 vcc, 0x4138aa3b, v177
	s_cmp_eq_u64 vcc, exec
	s_cbranch_scc0 .Lat_rare1_10

; template <bool FIRST> __device__ __forceinline__ void partialSM(f32x16& p0, f32x16& p1, float& mhat, f32x16& negm, float& alpha) {
;   float pa = fmaxf(fmaxf(p0[0], p0[1]), p1[0]), pb = fmaxf(fmaxf(p0[2], p0[3]), p1[1]); pa = fmaxf(fmaxf(pa, p1[2]), p1[3]);
; #pragma unroll
;   for (int r = 4; r < 16; r += 4) { pa = fmaxf(fmaxf(pa, p0[r]), p0[r + 1]); pb = fmaxf(fmaxf(pb, p0[r + 2]), p0[r + 3]); pa = fmaxf(fmaxf(pa, p1[r]), p1[r + 1]); pb = fmaxf(fmaxf(pb, p1[r + 2]), p1[r + 3]); }
;   float pmax = fmaxf(pa, pb);
;   { auto rr = __builtin_amdgcn_permlane32_swap(__float_as_uint(pmax), __float_as_uint(pmax), false, false);
;     pmax = fmaxf(__uint_as_float(rr[0]), __uint_as_float(rr[1])); }
;   if (!FIRST && __builtin_expect(__all(pmax <= THRL), 1)) { alpha = 1.f; }
;   else { const float d = FIRST ? pmax : fmaxf(pmax, 0.f); mhat += d; alpha = FIRST ? 1.f : __builtin_amdgcn_exp2f(-d);
; #pragma unroll
;     for (int r = 0; r < 16; ++r) { p0[r] -= d; p1[r] -= d; }
; #pragma unroll
;     for (int r = 0; r < 16; ++r) negm[r] = -mhat; }
; #pragma unroll
;   for (int r = 0; r < 16; ++r) p0[r] = __builtin_amdgcn_exp2f(p0[r]);
; }
; __device__ __forceinline__ void finishSM(f32x16& p0, f32x16& p1, float alpha, float& l_reg, bf16x8& pa0, bf16x8& pa1, bf16x8& pa2, bf16x8& pa3) {
; #pragma unroll
;   for (int r = 0; r < 16; ++r) p1[r] = __builtin_amdgcn_exp2f(p1[r]);
;   float ps = 0;
; #pragma unroll
;   for (int r = 0; r < 16; ++r) ps += p0[r];
; #pragma unroll
;   for (int r = 0; r < 16; ++r) ps += p1[r];
;   { auto rr = __builtin_amdgcn_permlane32_swap(__float_as_uint(ps), __float_as_uint(ps), false, false);
;     ps = __uint_as_float(rr[0]) + __uint_as_float(rr[1]); }
;   l_reg = l_reg * alpha + ps;
;     ...
;   PK4(p0, 0, pa0); PK4(p0, 8, pa1); PK4(p1, 0, pa2); PK4(p1, 8, pa3);
;     ...
; }
; __device__ __forceinline__ void qkt(f32x16& p0, f32x16& p1, const bf16_t* Ks, const bf16x8* qr, const f32x16& negm, int r32, int hi) {
;   p0 = negm; p1 = negm;
; #pragma unroll
;   for (int d0 = 0; d0 < 6; ++d0) { int cb = (d0 * 16 + hi * 8) * 2;
;     bf16x8 b0 = *reinterpret_cast<const bf16x8*>((const char*)Ks + KSWZ(r32, cb));
;     bf16x8 b1 = *reinterpret_cast<const bf16x8*>((const char*)Ks + KSWZ(32 + r32, cb));
;     p0 = __builtin_amdgcn_mfma_f32_32x32x16_bf16(b0, qr[d0], p0, 0, 0, 0);
;     p1 = __builtin_amdgcn_mfma_f32_32x32x16_bf16(b1, qr[d0], p1, 0, 0, 0); }
; }
.Lat_rr_12:
	s_waitcnt lgkmcnt(0)
	s_barrier
	ds_read_b128 v[200:203], v142 offset:0
	ds_read_b128 v[204:207], v142 offset:8192
	ds_read_b128 v[208:211], v143 offset:0
	ds_read_b128 v[212:215], v143 offset:8192
	s_add_i32 m0, s6, 49152
	s_mov_b64 exec, s[20:21]
	global_load_lds_dwordx4 v146, s[14:15]
	s_add_i32 m0, s6, 50176
	s_mov_b64 exec, s[22:23]
	global_load_lds_dwordx4 v147, s[14:15]
	s_add_i32 m0, s7, 16384
	s_mov_b64 exec, -1
	global_load_lds_dwordx4 v149, s[14:15]
	v_add_u32_e32 v146, v146, v148
	v_add_u32_e32 v147, v147, v217
	v_add_u32_e32 v149, 0x38000, v149
	v_mfma_f32_32x32x16_bf16 v[34:49], v[184:187], v[114:117], v[98:113]
	ds_read_b128 v[184:187], v144 offset:0
	v_exp_f32_e32 v82, v82
	v_exp_f32_e32 v83, v83
	v_exp_f32_e32 v84, v84
	v_exp_f32_e32 v85, v85
	v_exp_f32_e32 v86, v86
	v_mfma_f32_32x32x16_bf16 v[50:65], v[188:191], v[114:117], v[98:113]
	ds_read_b128 v[188:191], v144 offset:8192
	v_exp_f32_e32 v87, v87
	v_exp_f32_e32 v88, v88
	v_exp_f32_e32 v89, v89
	v_exp_f32_e32 v90, v90
	v_exp_f32_e32 v91, v91
	v_mfma_f32_32x32x16_bf16 v[34:49], v[192:195], v[118:121], v[34:49]
	ds_read_b128 v[192:195], v145 offset:0
	v_exp_f32_e32 v92, v92
	v_exp_f32_e32 v93, v93
	v_exp_f32_e32 v94, v94
	v_exp_f32_e32 v95, v95
	v_exp_f32_e32 v96, v96
	v_mfma_f32_32x32x16_bf16 v[50:65], v[196:199], v[118:121], v[50:65]
	ds_read_b128 v[196:199], v145 offset:8192
	v_exp_f32_e32 v97, v97
	v_cvt_pk_bf16_f32 v158, v66, v67
	v_cvt_pk_bf16_f32 v159, v68, v69
	v_cvt_pk_bf16_f32 v160, v70, v71
	v_cvt_pk_bf16_f32 v161, v72, v73
	s_waitcnt lgkmcnt(6)
	v_mfma_f32_32x32x16_bf16 v[34:49], v[200:203], v[122:125], v[34:49]
	ds_read_b64_tr_b16 v[200:201], v150 offset:57344
	ds_read_b64_tr_b16 v[202:203], v150 offset:59392
	v_cvt_pk_bf16_f32 v162, v74, v75
	v_cvt_pk_bf16_f32 v163, v76, v77
	v_cvt_pk_bf16_f32 v164, v78, v79
	v_cvt_pk_bf16_f32 v165, v80, v81
	v_permlane32_swap_b32_e32 v158, v160
	v_mfma_f32_32x32x16_bf16 v[50:65], v[204:207], v[122:125], v[50:65]
	ds_read_b64_tr_b16 v[204:205], v150 offset:57856
	ds_read_b64_tr_b16 v[206:207], v150 offset:59904
	v_permlane32_swap_b32_e32 v159, v161
	v_permlane32_swap_b32_e32 v162, v164
	v_permlane32_swap_b32_e32 v163, v165
	v_add_f32_e32 v181, v181, v82
	v_add_f32_e32 v182, v182, v83
	s_waitcnt lgkmcnt(8)
	v_mfma_f32_32x32x16_bf16 v[34:49], v[208:211], v[126:129], v[34:49]
	ds_read_b64_tr_b16 v[208:209], v150 offset:61440
	ds_read_b64_tr_b16 v[210:211], v150 offset:63488
	v_add_f32_e32 v183, v183, v84
	v_add_f32_e32 v216, v216, v85
	v_add_f32_e32 v181, v181, v86
	v_add_f32_e32 v182, v182, v87
	v_add_f32_e32 v183, v183, v88
	v_mfma_f32_32x32x16_bf16 v[50:65], v[212:215], v[126:129], v[50:65]
	ds_read_b64_tr_b16 v[212:213], v150 offset:61952
	ds_read_b64_tr_b16 v[214:215], v150 offset:64000
	v_add_f32_e32 v216, v216, v89
	v_add_f32_e32 v181, v181, v90
	v_add_f32_e32 v182, v182, v91
	v_add_f32_e32 v183, v183, v92
	v_add_f32_e32 v216, v216, v93
	s_waitcnt lgkmcnt(10)
	v_mfma_f32_32x32x16_bf16 v[34:49], v[184:187], v[130:133], v[34:49]
	ds_read_b64_tr_b16 v[184:185], v150 offset:49152
	ds_read_b64_tr_b16 v[186:187], v150 offset:51200
	v_add_f32_e32 v181, v181, v94
	v_add_f32_e32 v182, v182, v95
	v_add_f32_e32 v183, v183, v96
	v_add_f32_e32 v216, v216, v97
	v_add_f32_e32 v181, v181, v182
	v_mfma_f32_32x32x16_bf16 v[50:65], v[188:191], v[130:133], v[50:65]
	ds_read_b64_tr_b16 v[188:189], v150 offset:49664
	ds_read_b64_tr_b16 v[190:191], v150 offset:51712
	v_add_f32_e32 v183, v183, v216
	v_add_f32_e32 v181, v181, v183
	v_add_f32_e32 v174, v174, v181
	v_cvt_pk_bf16_f32 v166, v82, v83
	v_cvt_pk_bf16_f32 v167, v84, v85
	s_waitcnt lgkmcnt(12)
	v_mfma_f32_32x32x16_bf16 v[34:49], v[192:195], v[134:137], v[34:49]
	ds_read_b64_tr_b16 v[192:193], v150 offset:53248
	ds_read_b64_tr_b16 v[194:195], v150 offset:55296
	v_cvt_pk_bf16_f32 v168, v86, v87
	v_cvt_pk_bf16_f32 v169, v88, v89
	v_cvt_pk_bf16_f32 v170, v90, v91
	v_cvt_pk_bf16_f32 v171, v92, v93
	v_cvt_pk_bf16_f32 v172, v94, v95
	v_mfma_f32_32x32x16_bf16 v[50:65], v[196:199], v[134:137], v[50:65]
	ds_read_b64_tr_b16 v[196:197], v150 offset:53760
	s_waitcnt lgkmcnt(14)
	ds_read_b64_tr_b16 v[198:199], v150 offset:55808
	v_cvt_pk_bf16_f32 v173, v96, v97
	v_permlane32_swap_b32_e32 v166, v168
	v_permlane32_swap_b32_e32 v167, v169
	v_permlane32_swap_b32_e32 v170, v172
	v_permlane32_swap_b32_e32 v171, v173
	s_waitcnt lgkmcnt(4)
	v_mfma_f32_32x32x16_bf16 v[2:17], v[158:161], v[184:187], v[2:17]
	ds_read_b128 v[184:187], v140 offset:16384
	v_max3_f32 v177, v34, v35, v36
	v_max3_f32 v178, v37, v38, v39
	v_max3_f32 v177, v177, v40, v41
	v_mfma_f32_32x32x16_bf16 v[18:33], v[158:161], v[188:191], v[18:33]
	ds_read_b128 v[188:191], v140 offset:24576
	v_max3_f32 v178, v178, v42, v43
	v_max3_f32 v177, v177, v44, v45
	v_max3_f32 v178, v178, v46, v47
	v_max3_f32 v177, v177, v48, v49
	v_max3_f32 v178, v178, v50, v51
	v_max3_f32 v177, v177, v52, v53
	s_waitcnt lgkmcnt(2)
	v_mfma_f32_32x32x16_bf16 v[2:17], v[162:165], v[192:195], v[2:17]
	ds_read_b128 v[192:195], v141 offset:16384
	v_max3_f32 v178, v178, v54, v55
	v_max3_f32 v177, v177, v56, v57
	v_max3_f32 v178, v178, v58, v59
	v_max3_f32 v177, v177, v60, v61
	v_max3_f32 v178, v178, v62, v63
	v_max3_f32 v177, v177, v64, v65
	v_mfma_f32_32x32x16_bf16 v[18:33], v[162:165], v[196:199], v[18:33]
	ds_read_b128 v[196:199], v141 offset:24576
	v_max_f32_e32 v177, v177, v178
	v_mov_b32_e32 v178, v177
	s_nop 1
	v_permlane32_swap_b32_e32 v177, v178
	v_max_f32_e32 v177, v177, v178
	v_cmp_ge_f32_e32 vcc, 0x4138aa3b, v177
	s_cmp_eq_u64 vcc, exec
	s_cbranch_scc0 .Lat_rare1_14

; template <bool FIRST> __device__ __forceinline__ void partialSM(f32x16& p0, f32x16& p1, float& mhat, f32x16& negm, float& alpha) {
;   float pa = fmaxf(fmaxf(p0[0], p0[1]), p1[0]), pb = fmaxf(fmaxf(p0[2], p0[3]), p1[1]); pa = fmaxf(fmaxf(pa, p1[2]), p1[3]);
; #pragma unroll
;   for (int r = 4; r < 16; r += 4) { pa = fmaxf(fmaxf(pa, p0[r]), p0[r + 1]); pb = fmaxf(fmaxf(pb, p0[r + 2]), p0[r + 3]); pa = fmaxf(fmaxf(pa, p1[r]), p1[r + 1]); pb = fmaxf(fmaxf(pb, p1[r + 2]), p1[r + 3]); }
;   float pmax = fmaxf(pa, pb);
;   { auto rr = __builtin_amdgcn_permlane32_swap(__float_as_uint(pmax), __float_as_uint(pmax), false, false);
;     pmax = fmaxf(__uint_as_float(rr[0]), __uint_as_float(rr[1])); }
;   if (!FIRST && __builtin_expect(__all(pmax <= THRL), 1)) { alpha = 1.f; }
;   else { const float d = FIRST ? pmax : fmaxf(pmax, 0.f); mhat += d; alpha = FIRST ? 1.f : __builtin_amdgcn_exp2f(-d);
; #pragma unroll
;     for (int r = 0; r < 16; ++r) { p0[r] -= d; p1[r] -= d; }
; #pragma unroll
;     for (int r = 0; r < 16; ++r) negm[r] = -mhat; }
; #pragma unroll
;   for (int r = 0; r < 16; ++r) p0[r] = __builtin_amdgcn_exp2f(p0[r]);
; }
; __device__ __forceinline__ void finishSM(f32x16& p0, f32x16& p1, float alpha, float& l_reg, bf16x8& pa0, bf16x8& pa1, bf16x8& pa2, bf16x8& pa3) {
; #pragma unroll
;   for (int r = 0; r < 16; ++r) p1[r] = __builtin_amdgcn_exp2f(p1[r]);
;   float ps = 0;
; #pragma unroll
;   for (int r = 0; r < 16; ++r) ps += p0[r];
; #pragma unroll
;   for (int r = 0; r < 16; ++r) ps += p1[r];
;   { auto rr = __builtin_amdgcn_permlane32_swap(__float_as_uint(ps), __float_as_uint(ps), false, false);
;     ps = __uint_as_float(rr[0]) + __uint_as_float(rr[1]); }
;   l_reg = l_reg * alpha + ps;
;     ...
;   PK4(p0, 0, pa0); PK4(p0, 8, pa1); PK4(p1, 0, pa2); PK4(p1, 8, pa3);
;     ...
; }
; __device__ __forceinline__ void qkt(f32x16& p0, f32x16& p1, const bf16_t* Ks, const bf16x8* qr, const f32x16& negm, int r32, int hi) {
;   p0 = negm; p1 = negm;
; #pragma unroll
;   for (int d0 = 0; d0 < 6; ++d0) { int cb = (d0 * 16 + hi * 8) * 2;
;     bf16x8 b0 = *reinterpret_cast<const bf16x8*>((const char*)Ks + KSWZ(r32, cb));
;     bf16x8 b1 = *reinterpret_cast<const bf16x8*>((const char*)Ks + KSWZ(32 + r32, cb));
;     p0 = __builtin_amdgcn_mfma_f32_32x32x16_bf16(b0, qr[d0], p0, 0, 0, 0);
;     p1 = __builtin_amdgcn_mfma_f32_32x32x16_bf16(b1, qr[d0], p1, 0, 0, 0); }
; }
.Lat_rr_16:
	s_waitcnt lgkmcnt(0)
	s_barrier
	s_add_i32 s8, s8, 1
	s_cmp_lt_u32 s8, 31
	s_cbranch_scc1 .Lat_loop
	ds_read_b128 v[200:203], v142 offset:16384
	ds_read_b128 v[204:207], v142 offset:24576
	ds_read_b128 v[208:211], v143 offset:16384
	ds_read_b128 v[212:215], v143 offset:24576
	s_add_i32 m0, s7, 32768
	s_mov_b64 exec, -1
	global_load_lds_dwordx4 v149, s[14:15]
	v_add_u32_e32 v149, 0x38000, v149
	v_mfma_f32_32x32x16_bf16 v[66:81], v[184:187], v[114:117], v[98:113]
	ds_read_b128 v[184:187], v144 offset:16384
	v_exp_f32_e32 v50, v50
	v_exp_f32_e32 v51, v51
	v_exp_f32_e32 v52, v52
	v_exp_f32_e32 v53, v53
	v_exp_f32_e32 v54, v54
	v_mfma_f32_32x32x16_bf16 v[82:97], v[188:191], v[114:117], v[98:113]
	ds_read_b128 v[188:191], v144 offset:24576
	v_exp_f32_e32 v55, v55
	v_exp_f32_e32 v56, v56
	v_exp_f32_e32 v57, v57
	v_exp_f32_e32 v58, v58
	v_exp_f32_e32 v59, v59
	v_mfma_f32_32x32x16_bf16 v[66:81], v[192:195], v[118:121], v[66:81]
	ds_read_b128 v[192:195], v145 offset:16384
	v_exp_f32_e32 v60, v60
	v_exp_f32_e32 v61, v61
	v_exp_f32_e32 v62, v62
	v_exp_f32_e32 v63, v63
	v_exp_f32_e32 v64, v64
	v_mfma_f32_32x32x16_bf16 v[82:97], v[196:199], v[118:121], v[82:97]
	ds_read_b128 v[196:199], v145 offset:24576
	v_exp_f32_e32 v65, v65
	v_cvt_pk_bf16_f32 v158, v34, v35
	v_cvt_pk_bf16_f32 v159, v36, v37
	v_cvt_pk_bf16_f32 v160, v38, v39
	v_cvt_pk_bf16_f32 v161, v40, v41
	s_waitcnt lgkmcnt(6)
	v_mfma_f32_32x32x16_bf16 v[66:81], v[200:203], v[122:125], v[66:81]
	ds_read_b64_tr_b16 v[200:201], v150 offset:8192
	ds_read_b64_tr_b16 v[202:203], v150 offset:10240
	v_cvt_pk_bf16_f32 v162, v42, v43
	v_cvt_pk_bf16_f32 v163, v44, v45
	v_cvt_pk_bf16_f32 v164, v46, v47
	v_cvt_pk_bf16_f32 v165, v48, v49
	v_permlane32_swap_b32_e32 v158, v160
	v_mfma_f32_32x32x16_bf16 v[82:97], v[204:207], v[122:125], v[82:97]
	ds_read_b64_tr_b16 v[204:205], v150 offset:8704
	ds_read_b64_tr_b16 v[206:207], v150 offset:10752
	v_permlane32_swap_b32_e32 v159, v161
	v_permlane32_swap_b32_e32 v162, v164
	v_permlane32_swap_b32_e32 v163, v165
	v_add_f32_e32 v181, v181, v50
	v_add_f32_e32 v182, v182, v51
	s_waitcnt lgkmcnt(8)
	v_mfma_f32_32x32x16_bf16 v[66:81], v[208:211], v[126:129], v[66:81]
	ds_read_b64_tr_b16 v[208:209], v150 offset:12288
	ds_read_b64_tr_b16 v[210:211], v150 offset:14336
	v_add_f32_e32 v183, v183, v52
	v_add_f32_e32 v216, v216, v53
	v_add_f32_e32 v181, v181, v54
	v_add_f32_e32 v182, v182, v55
	v_add_f32_e32 v183, v183, v56
	v_mfma_f32_32x32x16_bf16 v[82:97], v[212:215], v[126:129], v[82:97]
	ds_read_b64_tr_b16 v[212:213], v150 offset:12800
	ds_read_b64_tr_b16 v[214:215], v150 offset:14848
	v_add_f32_e32 v216, v216, v57
	v_add_f32_e32 v181, v181, v58
	v_add_f32_e32 v182, v182, v59
	v_add_f32_e32 v183, v183, v60
	v_add_f32_e32 v216, v216, v61
	s_waitcnt lgkmcnt(10)
	v_mfma_f32_32x32x16_bf16 v[66:81], v[184:187], v[130:133], v[66:81]
	ds_read_b64_tr_b16 v[184:185], v150 offset:0
	ds_read_b64_tr_b16 v[186:187], v150 offset:2048
	v_add_f32_e32 v181, v181, v62
	v_add_f32_e32 v182, v182, v63
	v_add_f32_e32 v183, v183, v64
	v_add_f32_e32 v216, v216, v65
	v_add_f32_e32 v181, v181, v182
	v_mfma_f32_32x32x16_bf16 v[82:97], v[188:191], v[130:133], v[82:97]
	ds_read_b64_tr_b16 v[188:189], v150 offset:512
	ds_read_b64_tr_b16 v[190:191], v150 offset:2560
	v_add_f32_e32 v183, v183, v216
	v_add_f32_e32 v181, v181, v183
	v_add_f32_e32 v174, v174, v181
	v_cvt_pk_bf16_f32 v166, v50, v51
	v_cvt_pk_bf16_f32 v167, v52, v53
	s_waitcnt lgkmcnt(12)
	v_mfma_f32_32x32x16_bf16 v[66:81], v[192:195], v[134:137], v[66:81]
	ds_read_b64_tr_b16 v[192:193], v150 offset:4096
	ds_read_b64_tr_b16 v[194:195], v150 offset:6144
	v_cvt_pk_bf16_f32 v168, v54, v55
	v_cvt_pk_bf16_f32 v169, v56, v57
	v_cvt_pk_bf16_f32 v170, v58, v59
	v_cvt_pk_bf16_f32 v171, v60, v61
	v_cvt_pk_bf16_f32 v172, v62, v63
	v_mfma_f32_32x32x16_bf16 v[82:97], v[196:199], v[134:137], v[82:97]
	ds_read_b64_tr_b16 v[196:197], v150 offset:4608
	s_waitcnt lgkmcnt(14)
	ds_read_b64_tr_b16 v[198:199], v150 offset:6656
	v_cvt_pk_bf16_f32 v173, v64, v65
	v_permlane32_swap_b32_e32 v166, v168
	v_permlane32_swap_b32_e32 v167, v169
	v_permlane32_swap_b32_e32 v170, v172
	v_permlane32_swap_b32_e32 v171, v173
	s_waitcnt lgkmcnt(4)
	v_mfma_f32_32x32x16_bf16 v[2:17], v[158:161], v[184:187], v[2:17]
	ds_read_b128 v[184:187], v140 offset:32768
	v_max3_f32 v177, v66, v67, v68
	v_max3_f32 v178, v69, v70, v71
	v_max3_f32 v177, v177, v72, v73
	v_mfma_f32_32x32x16_bf16 v[18:33], v[158:161], v[188:191], v[18:33]
	ds_read_b128 v[188:191], v140 offset:40960
	v_max3_f32 v178, v178, v74, v75
	v_max3_f32 v177, v177, v76, v77
	v_max3_f32 v178, v178, v78, v79
	v_max3_f32 v177, v177, v80, v81
	v_max3_f32 v178, v178, v82, v83
	v_max3_f32 v177, v177, v84, v85
	s_waitcnt lgkmcnt(2)
	v_mfma_f32_32x32x16_bf16 v[2:17], v[162:165], v[192:195], v[2:17]
	ds_read_b128 v[192:195], v141 offset:32768
	v_max3_f32 v178, v178, v86, v87
	v_max3_f32 v177, v177, v88, v89
	v_max3_f32 v178, v178, v90, v91
	v_max3_f32 v177, v177, v92, v93
	v_max3_f32 v178, v178, v94, v95
	v_max3_f32 v177, v177, v96, v97
	v_mfma_f32_32x32x16_bf16 v[18:33], v[162:165], v[196:199], v[18:33]
	ds_read_b128 v[196:199], v141 offset:40960
	v_max_f32_e32 v177, v177, v178
	v_mov_b32_e32 v178, v177
	s_nop 1
	v_permlane32_swap_b32_e32 v177, v178
	v_max_f32_e32 v177, v177, v178
	v_cmp_ge_f32_e32 vcc, 0x4138aa3b, v177
	s_cmp_eq_u64 vcc, exec
	s_cbranch_scc0 .Lat_rare1_18
; template <bool FIRST> __device__ __forceinline__ void partialSM(f32x16& p0, f32x16& p1, float& mhat, f32x16& negm, float& alpha) {
;   float pa = fmaxf(fmaxf(p0[0], p0[1]), p1[0]), pb = fmaxf(fmaxf(p0[2], p0[3]), p1[1]); pa = fmaxf(fmaxf(pa, p1[2]), p1[3]);
; #pragma unroll
;   for (int r = 4; r < 16; r += 4) { pa = fmaxf(fmaxf(pa, p0[r]), p0[r + 1]); pb = fmaxf(fmaxf(pb, p0[r + 2]), p0[r + 3]); pa = fmaxf(fmaxf(pa, p1[r]), p1[r + 1]); pb = fmaxf(fmaxf(pb, p1[r + 2]), p1[r + 3]); }
;   float pmax = fmaxf(pa, pb);
;   { auto rr = __builtin_amdgcn_permlane32_swap(__float_as_uint(pmax), __float_as_uint(pmax), false, false);
;     pmax = fmaxf(__uint_as_float(rr[0]), __uint_as_float(rr[1])); }
;   if (!FIRST && __builtin_expect(__all(pmax <= THRL), 1)) { alpha = 1.f; }
;   else { const float d = FIRST ? pmax : fmaxf(pmax, 0.f); mhat += d; alpha = FIRST ? 1.f : __builtin_amdgcn_exp2f(-d);
; #pragma unroll
;     for (int r = 0; r < 16; ++r) { p0[r] -= d; p1[r] -= d; }
; #pragma unroll
;     for (int r = 0; r < 16; ++r) negm[r] = -mhat; }
; #pragma unroll
;   for (int r = 0; r < 16; ++r) p0[r] = __builtin_amdgcn_exp2f(p0[r]);
; }
; __device__ __forceinline__ void finishSM(f32x16& p0, f32x16& p1, float alpha, float& l_reg, bf16x8& pa0, bf16x8& pa1, bf16x8& pa2, bf16x8& pa3) {
; #pragma unroll
;   for (int r = 0; r < 16; ++r) p1[r] = __builtin_amdgcn_exp2f(p1[r]);
;   float ps = 0;
; #pragma unroll
;   for (int r = 0; r < 16; ++r) ps += p0[r];
; #pragma unroll
;   for (int r = 0; r < 16; ++r) ps += p1[r];
;   { auto rr = __builtin_amdgcn_permlane32_swap(__float_as_uint(ps), __float_as_uint(ps), false, false);
;     ps = __uint_as_float(rr[0]) + __uint_as_float(rr[1]); }
;   l_reg = l_reg * alpha + ps;
;     ...
;   PK4(p0, 0, pa0); PK4(p0, 8, pa1); PK4(p1, 0, pa2); PK4(p1, 8, pa3);
;     ...
; }
; __device__ __forceinline__ void qkt(f32x16& p0, f32x16& p1, const bf16_t* Ks, const bf16x8* qr, const f32x16& negm, int r32, int hi) {
;   p0 = negm; p1 = negm;
; #pragma unroll
;   for (int d0 = 0; d0 < 6; ++d0) { int cb = (d0 * 16 + hi * 8) * 2;
;     bf16x8 b0 = *reinterpret_cast<const bf16x8*>((const char*)Ks + KSWZ(r32, cb));
;     bf16x8 b1 = *reinterpret_cast<const bf16x8*>((const char*)Ks + KSWZ(32 + r32, cb));
;     p0 = __builtin_amdgcn_mfma_f32_32x32x16_bf16(b0, qr[d0], p0, 0, 0, 0);
;     p1 = __builtin_amdgcn_mfma_f32_32x32x16_bf16(b1, qr[d0], p1, 0, 0, 0); }
; }
.Lat_ri_17:
	v_mfma_f32_32x32x16_bf16 v[2:17], v[166:169], v[200:203], v[2:17]
	v_exp_f32_e32 v66, v66
	v_exp_f32_e32 v67, v67
	v_exp_f32_e32 v68, v68
	v_exp_f32_e32 v69, v69
	v_exp_f32_e32 v70, v70
	v_exp_f32_e32 v71, v71
	v_exp_f32_e32 v72, v72
	v_mfma_f32_32x32x16_bf16 v[18:33], v[166:169], v[204:207], v[18:33]
	v_exp_f32_e32 v73, v73
	v_exp_f32_e32 v74, v74
	v_exp_f32_e32 v75, v75
	v_exp_f32_e32 v76, v76
	v_exp_f32_e32 v77, v77
	v_exp_f32_e32 v78, v78
	v_exp_f32_e32 v79, v79
	v_mfma_f32_32x32x16_bf16 v[2:17], v[170:173], v[208:211], v[2:17]
	v_exp_f32_e32 v80, v80
	v_exp_f32_e32 v81, v81
	v_add_f32_e32 v181, v66, v70
	v_add_f32_e32 v182, v67, v71
	v_add_f32_e32 v183, v68, v72
	v_add_f32_e32 v216, v69, v73
	v_add_f32_e32 v181, v181, v74
	v_mfma_f32_32x32x16_bf16 v[18:33], v[170:173], v[212:215], v[18:33]
	v_add_f32_e32 v182, v182, v75
	v_add_f32_e32 v183, v183, v76
	v_add_f32_e32 v216, v216, v77
	v_add_f32_e32 v181, v181, v78
	v_add_f32_e32 v182, v182, v79
	v_add_f32_e32 v183, v183, v80
	v_add_f32_e32 v216, v216, v81
	s_waitcnt vmcnt(1)
	s_cmp_lg_u32 s9, 0
	s_cbranch_scc1 .Lat_rare2_19
.Lat_rr_20:
	s_waitcnt lgkmcnt(0)
	s_barrier
	ds_read_b128 v[200:203], v142 offset:32768
	ds_read_b128 v[204:207], v142 offset:40960
	ds_read_b128 v[208:211], v143 offset:32768
	ds_read_b128 v[212:215], v143 offset:40960
	s_add_i32 m0, s7, 49152
	s_mov_b64 exec, -1
	global_load_lds_dwordx4 v149, s[14:15]
	v_add_u32_e32 v149, 0x38000, v149
	v_mfma_f32_32x32x16_bf16 v[34:49], v[184:187], v[114:117], v[98:113]
	ds_read_b128 v[184:187], v144 offset:32768
	v_exp_f32_e32 v82, v82
	v_exp_f32_e32 v83, v83
	v_exp_f32_e32 v84, v84
	v_exp_f32_e32 v85, v85
	v_exp_f32_e32 v86, v86
	v_mfma_f32_32x32x16_bf16 v[50:65], v[188:191], v[114:117], v[98:113]
	ds_read_b128 v[188:191], v144 offset:40960
	v_exp_f32_e32 v87, v87
	v_exp_f32_e32 v88, v88
	v_exp_f32_e32 v89, v89
	v_exp_f32_e32 v90, v90
	v_exp_f32_e32 v91, v91
	v_mfma_f32_32x32x16_bf16 v[34:49], v[192:195], v[118:121], v[34:49]
	ds_read_b128 v[192:195], v145 offset:32768
	v_exp_f32_e32 v92, v92
	v_exp_f32_e32 v93, v93
	v_exp_f32_e32 v94, v94
	v_exp_f32_e32 v95, v95
	v_exp_f32_e32 v96, v96
	v_mfma_f32_32x32x16_bf16 v[50:65], v[196:199], v[118:121], v[50:65]
	ds_read_b128 v[196:199], v145 offset:40960
	v_exp_f32_e32 v97, v97
	v_cvt_pk_bf16_f32 v158, v66, v67
	v_cvt_pk_bf16_f32 v159, v68, v69
	v_cvt_pk_bf16_f32 v160, v70, v71
	v_cvt_pk_bf16_f32 v161, v72, v73
	s_waitcnt lgkmcnt(6)
	v_mfma_f32_32x32x16_bf16 v[34:49], v[200:203], v[122:125], v[34:49]
	ds_read_b64_tr_b16 v[200:201], v150 offset:24576
	ds_read_b64_tr_b16 v[202:203], v150 offset:26624
	v_cvt_pk_bf16_f32 v162, v74, v75
	v_cvt_pk_bf16_f32 v163, v76, v77
	v_cvt_pk_bf16_f32 v164, v78, v79
	v_cvt_pk_bf16_f32 v165, v80, v81
	v_permlane32_swap_b32_e32 v158, v160
	v_mfma_f32_32x32x16_bf16 v[50:65], v[204:207], v[122:125], v[50:65]
	ds_read_b64_tr_b16 v[204:205], v150 offset:25088
	ds_read_b64_tr_b16 v[206:207], v150 offset:27136
	v_permlane32_swap_b32_e32 v159, v161
	v_permlane32_swap_b32_e32 v162, v164
	v_permlane32_swap_b32_e32 v163, v165
	v_add_f32_e32 v181, v181, v82
	v_add_f32_e32 v182, v182, v83
	s_waitcnt lgkmcnt(8)
	v_mfma_f32_32x32x16_bf16 v[34:49], v[208:211], v[126:129], v[34:49]
	ds_read_b64_tr_b16 v[208:209], v150 offset:28672
	ds_read_b64_tr_b16 v[210:211], v150 offset:30720
	v_add_f32_e32 v183, v183, v84
	v_add_f32_e32 v216, v216, v85
	v_add_f32_e32 v181, v181, v86
	v_add_f32_e32 v182, v182, v87
	v_add_f32_e32 v183, v183, v88
	v_mfma_f32_32x32x16_bf16 v[50:65], v[212:215], v[126:129], v[50:65]
	ds_read_b64_tr_b16 v[212:213], v150 offset:29184
	ds_read_b64_tr_b16 v[214:215], v150 offset:31232
	v_add_f32_e32 v216, v216, v89
	v_add_f32_e32 v181, v181, v90
	v_add_f32_e32 v182, v182, v91
	v_add_f32_e32 v183, v183, v92
	v_add_f32_e32 v216, v216, v93
	s_waitcnt lgkmcnt(10)
	v_mfma_f32_32x32x16_bf16 v[34:49], v[184:187], v[130:133], v[34:49]
	ds_read_b64_tr_b16 v[184:185], v150 offset:16384
	ds_read_b64_tr_b16 v[186:187], v150 offset:18432
	v_add_f32_e32 v181, v181, v94
	v_add_f32_e32 v182, v182, v95
	v_add_f32_e32 v183, v183, v96
	v_add_f32_e32 v216, v216, v97
	v_add_f32_e32 v181, v181, v182
	v_mfma_f32_32x32x16_bf16 v[50:65], v[188:191], v[130:133], v[50:65]
	ds_read_b64_tr_b16 v[188:189], v150 offset:16896
	ds_read_b64_tr_b16 v[190:191], v150 offset:18944
	v_add_f32_e32 v183, v183, v216
	v_add_f32_e32 v181, v181, v183
	v_add_f32_e32 v174, v174, v181
	v_cvt_pk_bf16_f32 v166, v82, v83
	v_cvt_pk_bf16_f32 v167, v84, v85
	s_waitcnt lgkmcnt(12)
	v_mfma_f32_32x32x16_bf16 v[34:49], v[192:195], v[134:137], v[34:49]
	ds_read_b64_tr_b16 v[192:193], v150 offset:20480
	ds_read_b64_tr_b16 v[194:195], v150 offset:22528
	v_cvt_pk_bf16_f32 v168, v86, v87
	v_cvt_pk_bf16_f32 v169, v88, v89
	v_cvt_pk_bf16_f32 v170, v90, v91
	v_cvt_pk_bf16_f32 v171, v92, v93
	v_cvt_pk_bf16_f32 v172, v94, v95
	v_mfma_f32_32x32x16_bf16 v[50:65], v[196:199], v[134:137], v[50:65]
	ds_read_b64_tr_b16 v[196:197], v150 offset:20992
	s_waitcnt lgkmcnt(14)
	ds_read_b64_tr_b16 v[198:199], v150 offset:23040
	v_cvt_pk_bf16_f32 v173, v96, v97
	v_permlane32_swap_b32_e32 v166, v168
	v_permlane32_swap_b32_e32 v167, v169
	v_permlane32_swap_b32_e32 v170, v172
	v_permlane32_swap_b32_e32 v171, v173
	s_waitcnt lgkmcnt(4)
	v_mfma_f32_32x32x16_bf16 v[2:17], v[158:161], v[184:187], v[2:17]
	ds_read_b128 v[184:187], v140 offset:49152
	v_max3_f32 v177, v34, v35, v36
	v_max3_f32 v178, v37, v38, v39
	v_max3_f32 v177, v177, v40, v41
	v_mfma_f32_32x32x16_bf16 v[18:33], v[158:161], v[188:191], v[18:33]
	ds_read_b128 v[188:191], v140 offset:57344
	v_max3_f32 v178, v178, v42, v43
	v_max3_f32 v177, v177, v44, v45
	v_max3_f32 v178, v178, v46, v47
	v_max3_f32 v177, v177, v48, v49
	v_max3_f32 v178, v178, v50, v51
	v_max3_f32 v177, v177, v52, v53
	s_waitcnt lgkmcnt(2)
	v_mfma_f32_32x32x16_bf16 v[2:17], v[162:165], v[192:195], v[2:17]
	ds_read_b128 v[192:195], v141 offset:49152
	v_max3_f32 v178, v178, v54, v55
	v_max3_f32 v177, v177, v56, v57
	v_max3_f32 v178, v178, v58, v59
	v_max3_f32 v177, v177, v60, v61
	v_max3_f32 v178, v178, v62, v63
	v_max3_f32 v177, v177, v64, v65
	v_mfma_f32_32x32x16_bf16 v[18:33], v[162:165], v[196:199], v[18:33]
	ds_read_b128 v[196:199], v141 offset:57344
	v_max_f32_e32 v177, v177, v178
	v_mov_b32_e32 v178, v177
	s_nop 1
	v_permlane32_swap_b32_e32 v177, v178
	v_max_f32_e32 v177, v177, v178
	v_cmp_ge_f32_e32 vcc, 0x4138aa3b, v177
	s_cmp_eq_u64 vcc, exec
	s_cbranch_scc0 .Lat_rare1_22
; template <bool FIRST> __device__ __forceinline__ void partialSM(f32x16& p0, f32x16& p1, float& mhat, f32x16& negm, float& alpha) {
;   float pa = fmaxf(fmaxf(p0[0], p0[1]), p1[0]), pb = fmaxf(fmaxf(p0[2], p0[3]), p1[1]); pa = fmaxf(fmaxf(pa, p1[2]), p1[3]);
; #pragma unroll
;   for (int r = 4; r < 16; r += 4) { pa = fmaxf(fmaxf(pa, p0[r]), p0[r + 1]); pb = fmaxf(fmaxf(pb, p0[r + 2]), p0[r + 3]); pa = fmaxf(fmaxf(pa, p1[r]), p1[r + 1]); pb = fmaxf(fmaxf(pb, p1[r + 2]), p1[r + 3]); }
;   float pmax = fmaxf(pa, pb);
;   { auto rr = __builtin_amdgcn_permlane32_swap(__float_as_uint(pmax), __float_as_uint(pmax), false, false);
;     pmax = fmaxf(__uint_as_float(rr[0]), __uint_as_float(rr[1])); }
;   if (!FIRST && __builtin_expect(__all(pmax <= THRL), 1)) { alpha = 1.f; }
;   else { const float d = FIRST ? pmax : fmaxf(pmax, 0.f); mhat += d; alpha = FIRST ? 1.f : __builtin_amdgcn_exp2f(-d);
; #pragma unroll
;     for (int r = 0; r < 16; ++r) { p0[r] -= d; p1[r] -= d; }
; #pragma unroll
;     for (int r = 0; r < 16; ++r) negm[r] = -mhat; }
; #pragma unroll
;   for (int r = 0; r < 16; ++r) p0[r] = __builtin_amdgcn_exp2f(p0[r]);
; }
; __device__ __forceinline__ void finishSM(f32x16& p0, f32x16& p1, float alpha, float& l_reg, bf16x8& pa0, bf16x8& pa1, bf16x8& pa2, bf16x8& pa3) {
; #pragma unroll
;   for (int r = 0; r < 16; ++r) p1[r] = __builtin_amdgcn_exp2f(p1[r]);
;   float ps = 0;
; #pragma unroll
;   for (int r = 0; r < 16; ++r) ps += p0[r];
; #pragma unroll
;   for (int r = 0; r < 16; ++r) ps += p1[r];
;   { auto rr = __builtin_amdgcn_permlane32_swap(__float_as_uint(ps), __float_as_uint(ps), false, false);
;     ps = __uint_as_float(rr[0]) + __uint_as_float(rr[1]); }
;   l_reg = l_reg * alpha + ps;
;     ...
;   PK4(p0, 0, pa0); PK4(p0, 8, pa1); PK4(p1, 0, pa2); PK4(p1, 8, pa3);
;     ...
; }
; __device__ __forceinline__ void qkt(f32x16& p0, f32x16& p1, const bf16_t* Ks, const bf16x8* qr, const f32x16& negm, int r32, int hi) {
;   p0 = negm; p1 = negm;
; #pragma unroll
;   for (int d0 = 0; d0 < 6; ++d0) { int cb = (d0 * 16 + hi * 8) * 2;
;     bf16x8 b0 = *reinterpret_cast<const bf16x8*>((const char*)Ks + KSWZ(r32, cb));
;     bf16x8 b1 = *reinterpret_cast<const bf16x8*>((const char*)Ks + KSWZ(32 + r32, cb));
;     p0 = __builtin_amdgcn_mfma_f32_32x32x16_bf16(b0, qr[d0], p0, 0, 0, 0);
;     p1 = __builtin_amdgcn_mfma_f32_32x32x16_bf16(b1, qr[d0], p1, 0, 0, 0); }
; }
.Lat_ri_21:
	v_mfma_f32_32x32x16_bf16 v[2:17], v[166:169], v[200:203], v[2:17]
	v_exp_f32_e32 v34, v34
	v_exp_f32_e32 v35, v35
	v_exp_f32_e32 v36, v36
	v_exp_f32_e32 v37, v37
	v_exp_f32_e32 v38, v38
	v_exp_f32_e32 v39, v39
	v_exp_f32_e32 v40, v40
	v_mfma_f32_32x32x16_bf16 v[18:33], v[166:169], v[204:207], v[18:33]
	v_exp_f32_e32 v41, v41
	v_exp_f32_e32 v42, v42
	v_exp_f32_e32 v43, v43
	v_exp_f32_e32 v44, v44
	v_exp_f32_e32 v45, v45
	v_exp_f32_e32 v46, v46
	v_exp_f32_e32 v47, v47
	v_mfma_f32_32x32x16_bf16 v[2:17], v[170:173], v[208:211], v[2:17]
	v_exp_f32_e32 v48, v48
	v_exp_f32_e32 v49, v49
	v_add_f32_e32 v181, v34, v38
	v_add_f32_e32 v182, v35, v39
	v_add_f32_e32 v183, v36, v40
	v_add_f32_e32 v216, v37, v41
	v_add_f32_e32 v181, v181, v42
	v_mfma_f32_32x32x16_bf16 v[18:33], v[170:173], v[212:215], v[18:33]
	v_add_f32_e32 v182, v182, v43
	v_add_f32_e32 v183, v183, v44
	v_add_f32_e32 v216, v216, v45
	v_add_f32_e32 v181, v181, v46
	v_add_f32_e32 v182, v182, v47
	v_add_f32_e32 v183, v183, v48
	v_add_f32_e32 v216, v216, v49
	s_waitcnt vmcnt(1)
	s_cmp_lg_u32 s9, 0
	s_cbranch_scc1 .Lat_rare2_23
.Lat_rr_24:
	s_waitcnt lgkmcnt(0)
	s_barrier
	ds_read_b128 v[200:203], v142 offset:49152
	ds_read_b128 v[204:207], v142 offset:57344
	ds_read_b128 v[208:211], v143 offset:49152
	ds_read_b128 v[212:215], v143 offset:57344
	v_mfma_f32_32x32x16_bf16 v[66:81], v[184:187], v[114:117], v[98:113]
	ds_read_b128 v[184:187], v144 offset:49152
	v_exp_f32_e32 v50, v50
	v_exp_f32_e32 v51, v51
	v_exp_f32_e32 v52, v52
	v_exp_f32_e32 v53, v53
	v_exp_f32_e32 v54, v54
	v_mfma_f32_32x32x16_bf16 v[82:97], v[188:191], v[114:117], v[98:113]
	ds_read_b128 v[188:191], v144 offset:57344
	v_exp_f32_e32 v55, v55
	v_exp_f32_e32 v56, v56
	v_exp_f32_e32 v57, v57
	v_exp_f32_e32 v58, v58
	v_exp_f32_e32 v59, v59
	v_mfma_f32_32x32x16_bf16 v[66:81], v[192:195], v[118:121], v[66:81]
	ds_read_b128 v[192:195], v145 offset:49152
	v_exp_f32_e32 v60, v60
	v_exp_f32_e32 v61, v61
	v_exp_f32_e32 v62, v62
	v_exp_f32_e32 v63, v63
	v_exp_f32_e32 v64, v64
	v_mfma_f32_32x32x16_bf16 v[82:97], v[196:199], v[118:121], v[82:97]
	ds_read_b128 v[196:199], v145 offset:57344
	v_exp_f32_e32 v65, v65
	v_cvt_pk_bf16_f32 v158, v34, v35
	v_cvt_pk_bf16_f32 v159, v36, v37
	v_cvt_pk_bf16_f32 v160, v38, v39
	v_cvt_pk_bf16_f32 v161, v40, v41
	s_waitcnt lgkmcnt(6)
	v_mfma_f32_32x32x16_bf16 v[66:81], v[200:203], v[122:125], v[66:81]
	ds_read_b64_tr_b16 v[200:201], v150 offset:40960
	ds_read_b64_tr_b16 v[202:203], v150 offset:43008
	v_cvt_pk_bf16_f32 v162, v42, v43
	v_cvt_pk_bf16_f32 v163, v44, v45
	v_cvt_pk_bf16_f32 v164, v46, v47
	v_cvt_pk_bf16_f32 v165, v48, v49
	v_permlane32_swap_b32_e32 v158, v160
	v_mfma_f32_32x32x16_bf16 v[82:97], v[204:207], v[122:125], v[82:97]
	ds_read_b64_tr_b16 v[204:205], v150 offset:41472
	ds_read_b64_tr_b16 v[206:207], v150 offset:43520
	v_permlane32_swap_b32_e32 v159, v161
	v_permlane32_swap_b32_e32 v162, v164
	v_permlane32_swap_b32_e32 v163, v165
	v_add_f32_e32 v181, v181, v50
	v_add_f32_e32 v182, v182, v51
	s_waitcnt lgkmcnt(8)
	v_mfma_f32_32x32x16_bf16 v[66:81], v[208:211], v[126:129], v[66:81]
	ds_read_b64_tr_b16 v[208:209], v150 offset:45056
	ds_read_b64_tr_b16 v[210:211], v150 offset:47104
	v_add_f32_e32 v183, v183, v52
	v_add_f32_e32 v216, v216, v53
	v_add_f32_e32 v181, v181, v54
	v_add_f32_e32 v182, v182, v55
	v_add_f32_e32 v183, v183, v56
	v_mfma_f32_32x32x16_bf16 v[82:97], v[212:215], v[126:129], v[82:97]
	ds_read_b64_tr_b16 v[212:213], v150 offset:45568
	ds_read_b64_tr_b16 v[214:215], v150 offset:47616
	v_add_f32_e32 v216, v216, v57
	v_add_f32_e32 v181, v181, v58
	v_add_f32_e32 v182, v182, v59
	v_add_f32_e32 v183, v183, v60
	v_add_f32_e32 v216, v216, v61
	s_waitcnt lgkmcnt(10)
	v_mfma_f32_32x32x16_bf16 v[66:81], v[184:187], v[130:133], v[66:81]
	ds_read_b64_tr_b16 v[184:185], v150 offset:32768
	ds_read_b64_tr_b16 v[186:187], v150 offset:34816
	v_add_f32_e32 v181, v181, v62
	v_add_f32_e32 v182, v182, v63
	v_add_f32_e32 v183, v183, v64
	v_add_f32_e32 v216, v216, v65
	v_add_f32_e32 v181, v181, v182
	v_mfma_f32_32x32x16_bf16 v[82:97], v[188:191], v[130:133], v[82:97]
	ds_read_b64_tr_b16 v[188:189], v150 offset:33280
	ds_read_b64_tr_b16 v[190:191], v150 offset:35328
	v_add_f32_e32 v183, v183, v216
	v_add_f32_e32 v181, v181, v183
	v_add_f32_e32 v174, v174, v181
	v_cvt_pk_bf16_f32 v166, v50, v51
	v_cvt_pk_bf16_f32 v167, v52, v53
	s_waitcnt lgkmcnt(12)
	v_mfma_f32_32x32x16_bf16 v[66:81], v[192:195], v[134:137], v[66:81]
	ds_read_b64_tr_b16 v[192:193], v150 offset:36864
	ds_read_b64_tr_b16 v[194:195], v150 offset:38912
	v_cvt_pk_bf16_f32 v168, v54, v55
	v_cvt_pk_bf16_f32 v169, v56, v57
	v_cvt_pk_bf16_f32 v170, v58, v59
	v_cvt_pk_bf16_f32 v171, v60, v61
	v_cvt_pk_bf16_f32 v172, v62, v63
	v_mfma_f32_32x32x16_bf16 v[82:97], v[196:199], v[134:137], v[82:97]
	ds_read_b64_tr_b16 v[196:197], v150 offset:37376
	s_waitcnt lgkmcnt(14)
	ds_read_b64_tr_b16 v[198:199], v150 offset:39424
	v_cvt_pk_bf16_f32 v173, v64, v65
	v_permlane32_swap_b32_e32 v166, v168
	v_permlane32_swap_b32_e32 v167, v169
	v_permlane32_swap_b32_e32 v170, v172
	v_permlane32_swap_b32_e32 v171, v173
	s_waitcnt lgkmcnt(4)
	v_mfma_f32_32x32x16_bf16 v[2:17], v[158:161], v[184:187], v[2:17]
	v_max3_f32 v177, v66, v67, v68
	v_max3_f32 v178, v69, v70, v71
	v_max3_f32 v177, v177, v72, v73
	v_mfma_f32_32x32x16_bf16 v[18:33], v[158:161], v[188:191], v[18:33]
	v_max3_f32 v178, v178, v74, v75
	v_max3_f32 v177, v177, v76, v77
	v_max3_f32 v178, v178, v78, v79
	v_max3_f32 v177, v177, v80, v81
	v_max3_f32 v178, v178, v82, v83
	v_max3_f32 v177, v177, v84, v85
	s_waitcnt lgkmcnt(0)
	v_mfma_f32_32x32x16_bf16 v[2:17], v[162:165], v[192:195], v[2:17]
	v_max3_f32 v178, v178, v86, v87
	v_max3_f32 v177, v177, v88, v89
	v_max3_f32 v178, v178, v90, v91
	v_max3_f32 v177, v177, v92, v93
	v_max3_f32 v178, v178, v94, v95
	v_max3_f32 v177, v177, v96, v97
	v_mfma_f32_32x32x16_bf16 v[18:33], v[162:165], v[196:199], v[18:33]
	v_max_f32_e32 v177, v177, v178
	v_mov_b32_e32 v178, v177
	s_nop 1
	v_permlane32_swap_b32_e32 v177, v178
	v_max_f32_e32 v177, v177, v178
	v_cmp_ge_f32_e32 vcc, 0x4138aa3b, v177
	s_cmp_eq_u64 vcc, exec
	s_cbranch_scc0 .Lat_rare1_26
; __device__ __forceinline__ void finishSM(f32x16& p0, f32x16& p1, float alpha, float& l_reg, bf16x8& pa0, bf16x8& pa1, bf16x8& pa2, bf16x8& pa3) {
; #pragma unroll
;   for (int r = 0; r < 16; ++r) p1[r] = __builtin_amdgcn_exp2f(p1[r]);
;   float ps = 0;
; #pragma unroll
;   for (int r = 0; r < 16; ++r) ps += p0[r];
; #pragma unroll
;   for (int r = 0; r < 16; ++r) ps += p1[r];
;   { auto rr = __builtin_amdgcn_permlane32_swap(__float_as_uint(ps), __float_as_uint(ps), false, false);
;     ps = __uint_as_float(rr[0]) + __uint_as_float(rr[1]); }
;   l_reg = l_reg * alpha + ps;
;     ...
;   PK4(p0, 0, pa0); PK4(p0, 8, pa1); PK4(p1, 0, pa2); PK4(p1, 8, pa3);
;     ...
; }
; __device__ __forceinline__ void qkt(f32x16& p0, f32x16& p1, const bf16_t* Ks, const bf16x8* qr, const f32x16& negm, int r32, int hi) {
;   p0 = negm; p1 = negm;
; #pragma unroll
;   for (int d0 = 0; d0 < 6; ++d0) { int cb = (d0 * 16 + hi * 8) * 2;
;     bf16x8 b0 = *reinterpret_cast<const bf16x8*>((const char*)Ks + KSWZ(r32, cb));
;     bf16x8 b1 = *reinterpret_cast<const bf16x8*>((const char*)Ks + KSWZ(32 + r32, cb));
;     p0 = __builtin_amdgcn_mfma_f32_32x32x16_bf16(b0, qr[d0], p0, 0, 0, 0);
;     p1 = __builtin_amdgcn_mfma_f32_32x32x16_bf16(b1, qr[d0], p1, 0, 0, 0); }
; }
; __device__ __forceinline__ int v_st(int k, int c) { const int kk = (k & ~0xC) | ((k & 4) << 1) | ((k & 8) >> 1); return ((kk >> 3) * 4 + (c >> 5)) * 512 + ((kk & 7) * 32 + (c & 31)) * 2; }
; __device__ __forceinline__ int v_rd_base(int lane) { return ((lane & 3) << 3) | (((lane >> 2) & 3) << 6) | (((lane >> 4) & 1) << 5) | (((lane >> 5) & 1) << 8); }
; template <int OFF> __device__ __forceinline__ s16x4 tr_read(int vb) {
;   s16x4 r; asm volatile("ds_read_b64_tr_b16 %0, %1 offset:%2" : "=&v"(r) : "v"(vb), "i"(OFF) : "memory"); return r;
; }
; template <int D0> __device__ __forceinline__ void pv_one(f32x16& od, int vb, bf16x8 pa0, bf16x8 pa1, bf16x8 pa2, bf16x8 pa3) {
;   const s16x4 l0 = tr_read<v_rd_off(D0, 0, 0)>(vb), h0 = tr_read<v_rd_off(D0, 0, 1)>(vb), l1 = tr_read<v_rd_off(D0, 1, 0)>(vb), h1 = tr_read<v_rd_off(D0, 1, 1)>(vb);
;   const s16x4 l2 = tr_read<v_rd_off(D0, 2, 0)>(vb), h2 = tr_read<v_rd_off(D0, 2, 1)>(vb), l3 = tr_read<v_rd_off(D0, 3, 0)>(vb), h3 = tr_read<v_rd_off(D0, 3, 1)>(vb);
;   asm volatile("s_waitcnt lgkmcnt(0)" ::: "memory"); SBAR();
;     ...
;   od = __builtin_amdgcn_mfma_f32_32x32x16_bf16(pa0, PK(l0, h0), od, 0, 0, 0);
.Lat_ri_25:
	v_mfma_f32_32x32x16_bf16 v[2:17], v[166:169], v[200:203], v[2:17]
	v_exp_f32_e32 v66, v66
	v_exp_f32_e32 v67, v67
	v_exp_f32_e32 v68, v68
	v_exp_f32_e32 v69, v69
	v_exp_f32_e32 v70, v70
	v_exp_f32_e32 v71, v71
	v_exp_f32_e32 v72, v72
	v_mfma_f32_32x32x16_bf16 v[18:33], v[166:169], v[204:207], v[18:33]
	v_exp_f32_e32 v73, v73
	v_exp_f32_e32 v74, v74
	v_exp_f32_e32 v75, v75
	v_exp_f32_e32 v76, v76
	v_exp_f32_e32 v77, v77
	v_exp_f32_e32 v78, v78
	v_exp_f32_e32 v79, v79
	v_mfma_f32_32x32x16_bf16 v[2:17], v[170:173], v[208:211], v[2:17]
	v_exp_f32_e32 v80, v80
	v_exp_f32_e32 v81, v81
	v_add_f32_e32 v181, v66, v70
	v_add_f32_e32 v182, v67, v71
	v_add_f32_e32 v183, v68, v72
	v_add_f32_e32 v216, v69, v73
	v_add_f32_e32 v181, v181, v74
	v_mfma_f32_32x32x16_bf16 v[18:33], v[170:173], v[212:215], v[18:33]
	v_add_f32_e32 v182, v182, v75
	v_add_f32_e32 v183, v183, v76
	v_add_f32_e32 v216, v216, v77
	v_add_f32_e32 v181, v181, v78
	v_add_f32_e32 v182, v182, v79
	v_add_f32_e32 v183, v183, v80
	v_add_f32_e32 v216, v216, v81
	s_waitcnt vmcnt(0)
	s_cmp_lg_u32 s9, 0
	s_cbranch_scc1 .Lat_rare2_27
.Lat_rr_28:
	s_barrier
	ds_read_b64_tr_b16 v[184:185], v150 offset:49152
	ds_read_b64_tr_b16 v[186:187], v150 offset:51200
	ds_read_b64_tr_b16 v[188:189], v150 offset:49664
	ds_read_b64_tr_b16 v[190:191], v150 offset:51712
	ds_read_b64_tr_b16 v[192:193], v150 offset:53248
	ds_read_b64_tr_b16 v[194:195], v150 offset:55296
	ds_read_b64_tr_b16 v[196:197], v150 offset:53760
	ds_read_b64_tr_b16 v[198:199], v150 offset:55808
	v_exp_f32_e32 v82, v82
	v_exp_f32_e32 v83, v83
	v_exp_f32_e32 v84, v84
	v_exp_f32_e32 v85, v85
	v_exp_f32_e32 v86, v86
	v_exp_f32_e32 v87, v87
	v_exp_f32_e32 v88, v88
	v_exp_f32_e32 v89, v89
	v_exp_f32_e32 v90, v90
	v_exp_f32_e32 v91, v91
	v_exp_f32_e32 v92, v92
	v_exp_f32_e32 v93, v93
	v_exp_f32_e32 v94, v94
	v_exp_f32_e32 v95, v95
	v_exp_f32_e32 v96, v96
	v_exp_f32_e32 v97, v97
	v_cvt_pk_bf16_f32 v158, v66, v67
	v_cvt_pk_bf16_f32 v159, v68, v69
	v_cvt_pk_bf16_f32 v160, v70, v71
	v_cvt_pk_bf16_f32 v161, v72, v73
	v_cvt_pk_bf16_f32 v162, v74, v75
	v_cvt_pk_bf16_f32 v163, v76, v77
	v_cvt_pk_bf16_f32 v164, v78, v79
	v_cvt_pk_bf16_f32 v165, v80, v81
	v_permlane32_swap_b32_e32 v158, v160
	v_permlane32_swap_b32_e32 v159, v161
	v_permlane32_swap_b32_e32 v162, v164
	v_permlane32_swap_b32_e32 v163, v165
	v_add_f32_e32 v181, v181, v82
	v_add_f32_e32 v182, v182, v83
	ds_read_b64_tr_b16 v[200:201], v150 offset:57344
	ds_read_b64_tr_b16 v[202:203], v150 offset:59392
	ds_read_b64_tr_b16 v[204:205], v150 offset:57856
	ds_read_b64_tr_b16 v[206:207], v150 offset:59904
	ds_read_b64_tr_b16 v[208:209], v150 offset:61440
	ds_read_b64_tr_b16 v[210:211], v150 offset:63488
	ds_read_b64_tr_b16 v[212:213], v150 offset:61952
	s_waitcnt lgkmcnt(14)
	ds_read_b64_tr_b16 v[214:215], v150 offset:64000
	v_add_f32_e32 v183, v183, v84
	v_add_f32_e32 v216, v216, v85
	v_add_f32_e32 v181, v181, v86
	v_add_f32_e32 v182, v182, v87
	v_add_f32_e32 v183, v183, v88
	v_add_f32_e32 v216, v216, v89
	v_add_f32_e32 v181, v181, v90
	v_add_f32_e32 v182, v182, v91
	v_add_f32_e32 v183, v183, v92
	v_add_f32_e32 v216, v216, v93
	v_add_f32_e32 v181, v181, v94
	v_add_f32_e32 v182, v182, v95
	v_add_f32_e32 v183, v183, v96
	v_add_f32_e32 v216, v216, v97
	v_add_f32_e32 v181, v181, v182
	v_add_f32_e32 v183, v183, v216
	v_add_f32_e32 v181, v181, v183
	v_add_f32_e32 v174, v174, v181
	v_cvt_pk_bf16_f32 v166, v82, v83
	v_cvt_pk_bf16_f32 v167, v84, v85
	v_cvt_pk_bf16_f32 v168, v86, v87
	v_cvt_pk_bf16_f32 v169, v88, v89
	v_cvt_pk_bf16_f32 v170, v90, v91
	v_cvt_pk_bf16_f32 v171, v92, v93
	v_cvt_pk_bf16_f32 v172, v94, v95
	v_cvt_pk_bf16_f32 v173, v96, v97
	v_permlane32_swap_b32_e32 v166, v168
	v_permlane32_swap_b32_e32 v167, v169
	v_permlane32_swap_b32_e32 v170, v172
	v_permlane32_swap_b32_e32 v171, v173
	s_waitcnt lgkmcnt(12)
	v_mfma_f32_32x32x16_bf16 v[2:17], v[158:161], v[184:187], v[2:17]
	v_mfma_f32_32x32x16_bf16 v[18:33], v[158:161], v[188:191], v[18:33]
	s_waitcnt lgkmcnt(8)
	v_mfma_f32_32x32x16_bf16 v[2:17], v[162:165], v[192:195], v[2:17]
	v_mfma_f32_32x32x16_bf16 v[18:33], v[162:165], v[196:199], v[18:33]
	s_waitcnt lgkmcnt(4)
	v_mfma_f32_32x32x16_bf16 v[2:17], v[166:169], v[200:203], v[2:17]
	v_mfma_f32_32x32x16_bf16 v[18:33], v[166:169], v[204:207], v[18:33]
	s_waitcnt lgkmcnt(0)
	v_mfma_f32_32x32x16_bf16 v[2:17], v[170:173], v[208:211], v[2:17]
	v_mfma_f32_32x32x16_bf16 v[18:33], v[170:173], v[212:215], v[18:33]
	s_waitcnt vmcnt(0)
	s_cmp_lg_u32 s9, 0
	s_cbranch_scc1 .Lat_rare2_30
; __device__ __forceinline__ unsigned f2bf(float f) { unsigned u = __builtin_bit_cast(unsigned, f); return (u + 0x7fffu + ((u >> 16) & 1u)) >> 16; }
; __device__ __forceinline__ int crow(int r, int hi) { return (r & 3) + 8 * (r >> 2) + 4 * hi; }
; __device__ __forceinline__ void attn_item(const bf16_t* __restrict__ Qb, const bf16_t* __restrict__ Kn, const bf16_t* __restrict__ Kr, const bf16_t* __restrict__ Vh,
;                                           const float* __restrict__ csq, bf16_t* __restrict__ Ob, int seq, char* lds) {
;     ...
;   __builtin_amdgcn_s_setprio(0);
;   if (hi == 0) li_l[r32] = l_reg; asm volatile("s_waitcnt lgkmcnt(0)" ::: "memory");
;   float rli[16];
; #pragma unroll
;   for (int r = 0; r < 16; ++r) rli[r] = __builtin_amdgcn_rcpf(li_l[crow(r, hi)]);
;   bf16_t* Ow = Ob + (long)(wid * QBLK) * DM;
; #pragma unroll
;   for (int r = 0; r < 16; ++r) { int orow = crow(r, hi);
; #pragma unroll
;     for (int d0 = 0; d0 < 2; ++d0) Ow[(long)orow * DM + d0 * 32 + r32] = (bf16_t)f2bf(o[d0][r] * rli[r]); }
.Lat_rr_31:
	s_barrier
	s_setprio 0
	s_nop 7
	s_nop 7
	v_mov_b32_e32 v177, v174
	s_nop 1
	v_permlane32_swap_b32_e32 v174, v177
	v_add_f32_e32 v174, v174, v177
	s_mov_b32 exec_hi, 0
	ds_write_b32 v175, v174
	s_mov_b64 exec, -1
	s_waitcnt lgkmcnt(0)
	ds_read_b128 v[184:187], v176 offset:0
	ds_read_b128 v[188:191], v176 offset:32
	ds_read_b128 v[192:195], v176 offset:64
	ds_read_b128 v[196:199], v176 offset:96
	v_and_b32_e32 v1, 63, v180
	v_and_b32_e32 v178, 31, v1
	v_lshrrev_b32_e32 v179, 5, v1
	s_lshl_b32 s30, s29, 16
	v_lshlrev_b32_e32 v177, 13, v179
	v_add_u32_e32 v177, s30, v177
	v_lshl_add_u32 v177, v178, 1, v177
	s_waitcnt lgkmcnt(0)
	v_rcp_f32_e32 v184, v184
	v_rcp_f32_e32 v185, v185
	v_rcp_f32_e32 v186, v186
	v_rcp_f32_e32 v187, v187
	v_rcp_f32_e32 v188, v188
	v_rcp_f32_e32 v189, v189
	v_rcp_f32_e32 v190, v190
	v_rcp_f32_e32 v191, v191
	v_rcp_f32_e32 v192, v192
	v_rcp_f32_e32 v193, v193
	v_rcp_f32_e32 v194, v194
	v_rcp_f32_e32 v195, v195
	v_rcp_f32_e32 v196, v196
	v_rcp_f32_e32 v197, v197
	v_rcp_f32_e32 v198, v198
	v_rcp_f32_e32 v199, v199
	s_nop 0
	v_add_u32_e32 v200, 0, v177
	v_add_u32_e32 v201, 4096, v177
	v_add_u32_e32 v202, 16384, v177
	v_add_u32_e32 v203, 20480, v177
	v_add_u32_e32 v204, 32768, v177
	v_add_u32_e32 v205, 36864, v177
	v_add_u32_e32 v206, 49152, v177
	v_add_u32_e32 v207, 53248, v177
	v_mul_f32_e32 v2, v2, v184
	v_bfe_u32 v1, v2, 16, 1
	v_add3_u32 v2, v2, v1, s25
	global_store_short_d16_hi v200, v2, s[26:27] offset:0
	v_mul_f32_e32 v18, v18, v184
	v_bfe_u32 v1, v18, 16, 1
	v_add3_u32 v18, v18, v1, s25
	global_store_short_d16_hi v200, v18, s[26:27] offset:64
	v_mul_f32_e32 v3, v3, v185
	v_bfe_u32 v1, v3, 16, 1
	v_add3_u32 v3, v3, v1, s25
	global_store_short_d16_hi v200, v3, s[26:27] offset:2048
	v_mul_f32_e32 v19, v19, v185
	v_bfe_u32 v1, v19, 16, 1
	v_add3_u32 v19, v19, v1, s25
	global_store_short_d16_hi v200, v19, s[26:27] offset:2112
	v_mul_f32_e32 v4, v4, v186
	v_bfe_u32 v1, v4, 16, 1
	v_add3_u32 v4, v4, v1, s25
	global_store_short_d16_hi v201, v4, s[26:27] offset:0
	v_mul_f32_e32 v20, v20, v186
	v_bfe_u32 v1, v20, 16, 1
	v_add3_u32 v20, v20, v1, s25
	global_store_short_d16_hi v201, v20, s[26:27] offset:64
	v_mul_f32_e32 v5, v5, v187
	v_bfe_u32 v1, v5, 16, 1
	v_add3_u32 v5, v5, v1, s25
	global_store_short_d16_hi v201, v5, s[26:27] offset:2048
	v_mul_f32_e32 v21, v21, v187
	v_bfe_u32 v1, v21, 16, 1
	v_add3_u32 v21, v21, v1, s25
	global_store_short_d16_hi v201, v21, s[26:27] offset:2112
	v_mul_f32_e32 v6, v6, v188
	v_bfe_u32 v1, v6, 16, 1
	v_add3_u32 v6, v6, v1, s25
	global_store_short_d16_hi v202, v6, s[26:27] offset:0
	v_mul_f32_e32 v22, v22, v188
	v_bfe_u32 v1, v22, 16, 1
	v_add3_u32 v22, v22, v1, s25
	global_store_short_d16_hi v202, v22, s[26:27] offset:64
	v_mul_f32_e32 v7, v7, v189
	v_bfe_u32 v1, v7, 16, 1
	v_add3_u32 v7, v7, v1, s25
	global_store_short_d16_hi v202, v7, s[26:27] offset:2048
	v_mul_f32_e32 v23, v23, v189
	v_bfe_u32 v1, v23, 16, 1
	v_add3_u32 v23, v23, v1, s25
	global_store_short_d16_hi v202, v23, s[26:27] offset:2112
	v_mul_f32_e32 v8, v8, v190
	v_bfe_u32 v1, v8, 16, 1
	v_add3_u32 v8, v8, v1, s25
	global_store_short_d16_hi v203, v8, s[26:27] offset:0
	v_mul_f32_e32 v24, v24, v190
	v_bfe_u32 v1, v24, 16, 1
	v_add3_u32 v24, v24, v1, s25
	global_store_short_d16_hi v203, v24, s[26:27] offset:64
	v_mul_f32_e32 v9, v9, v191
	v_bfe_u32 v1, v9, 16, 1
	v_add3_u32 v9, v9, v1, s25
	global_store_short_d16_hi v203, v9, s[26:27] offset:2048
	v_mul_f32_e32 v25, v25, v191
	v_bfe_u32 v1, v25, 16, 1
	v_add3_u32 v25, v25, v1, s25
	global_store_short_d16_hi v203, v25, s[26:27] offset:2112
	v_mul_f32_e32 v10, v10, v192
	v_bfe_u32 v1, v10, 16, 1
	v_add3_u32 v10, v10, v1, s25
	global_store_short_d16_hi v204, v10, s[26:27] offset:0
	v_mul_f32_e32 v26, v26, v192
	v_bfe_u32 v1, v26, 16, 1
	v_add3_u32 v26, v26, v1, s25
	global_store_short_d16_hi v204, v26, s[26:27] offset:64
	v_mul_f32_e32 v11, v11, v193
	v_bfe_u32 v1, v11, 16, 1
	v_add3_u32 v11, v11, v1, s25
	global_store_short_d16_hi v204, v11, s[26:27] offset:2048
	v_mul_f32_e32 v27, v27, v193
	v_bfe_u32 v1, v27, 16, 1
	v_add3_u32 v27, v27, v1, s25
	global_store_short_d16_hi v204, v27, s[26:27] offset:2112
	v_mul_f32_e32 v12, v12, v194
	v_bfe_u32 v1, v12, 16, 1
	v_add3_u32 v12, v12, v1, s25
	global_store_short_d16_hi v205, v12, s[26:27] offset:0
	v_mul_f32_e32 v28, v28, v194
	v_bfe_u32 v1, v28, 16, 1
	v_add3_u32 v28, v28, v1, s25
	global_store_short_d16_hi v205, v28, s[26:27] offset:64
	v_mul_f32_e32 v13, v13, v195
	v_bfe_u32 v1, v13, 16, 1
	v_add3_u32 v13, v13, v1, s25
	global_store_short_d16_hi v205, v13, s[26:27] offset:2048
	v_mul_f32_e32 v29, v29, v195
	v_bfe_u32 v1, v29, 16, 1
	v_add3_u32 v29, v29, v1, s25
	global_store_short_d16_hi v205, v29, s[26:27] offset:2112
	v_mul_f32_e32 v14, v14, v196
	v_bfe_u32 v1, v14, 16, 1
	v_add3_u32 v14, v14, v1, s25
	global_store_short_d16_hi v206, v14, s[26:27] offset:0
	v_mul_f32_e32 v30, v30, v196
	v_bfe_u32 v1, v30, 16, 1
	v_add3_u32 v30, v30, v1, s25
	global_store_short_d16_hi v206, v30, s[26:27] offset:64
	v_mul_f32_e32 v15, v15, v197
	v_bfe_u32 v1, v15, 16, 1
	v_add3_u32 v15, v15, v1, s25
	global_store_short_d16_hi v206, v15, s[26:27] offset:2048
	v_mul_f32_e32 v31, v31, v197
	v_bfe_u32 v1, v31, 16, 1
	v_add3_u32 v31, v31, v1, s25
	global_store_short_d16_hi v206, v31, s[26:27] offset:2112
	v_mul_f32_e32 v16, v16, v198
	v_bfe_u32 v1, v16, 16, 1
	v_add3_u32 v16, v16, v1, s25
	global_store_short_d16_hi v207, v16, s[26:27] offset:0
	v_mul_f32_e32 v32, v32, v198
	v_bfe_u32 v1, v32, 16, 1
	v_add3_u32 v32, v32, v1, s25
	global_store_short_d16_hi v207, v32, s[26:27] offset:64
	v_mul_f32_e32 v17, v17, v199
	v_bfe_u32 v1, v17, 16, 1
	v_add3_u32 v17, v17, v1, s25
	global_store_short_d16_hi v207, v17, s[26:27] offset:2048
	v_mul_f32_e32 v33, v33, v199
	v_bfe_u32 v1, v33, 16, 1
	v_add3_u32 v33, v33, v1, s25
	global_store_short_d16_hi v207, v33, s[26:27] offset:2112
	s_add_i32 s28, s28, s92
	s_cmpk_lt_i32 s28, 0x400
	s_cbranch_scc1 .Lat_item
	s_branch .Lat_done

.Lat_rareII:
	s_nop 15
	s_waitcnt lgkmcnt(0)
	ds_read_b128 v[200:203], v176 offset:128
	ds_read_b128 v[204:207], v176 offset:160
	ds_read_b128 v[208:211], v176 offset:192
	ds_read_b128 v[212:215], v176 offset:224
	s_waitcnt lgkmcnt(0)
	v_mul_f32_e32 v2, v2, v200
	v_mul_f32_e32 v3, v3, v201
	v_mul_f32_e32 v4, v4, v202
	v_mul_f32_e32 v5, v5, v203
	v_mul_f32_e32 v6, v6, v204
	v_mul_f32_e32 v7, v7, v205
	v_mul_f32_e32 v8, v8, v206
	v_mul_f32_e32 v9, v9, v207
	v_mul_f32_e32 v10, v10, v208
	v_mul_f32_e32 v11, v11, v209
	v_mul_f32_e32 v12, v12, v210
	v_mul_f32_e32 v13, v13, v211
	v_mul_f32_e32 v14, v14, v212
	v_mul_f32_e32 v15, v15, v213
	v_mul_f32_e32 v16, v16, v214
	v_mul_f32_e32 v17, v17, v215
	v_mul_f32_e32 v18, v18, v200
	v_mul_f32_e32 v19, v19, v201
	v_mul_f32_e32 v20, v20, v202
	v_mul_f32_e32 v21, v21, v203
	v_mul_f32_e32 v22, v22, v204
	v_mul_f32_e32 v23, v23, v205
	v_mul_f32_e32 v24, v24, v206
	v_mul_f32_e32 v25, v25, v207
	v_mul_f32_e32 v26, v26, v208
	v_mul_f32_e32 v27, v27, v209
	v_mul_f32_e32 v28, v28, v210
	v_mul_f32_e32 v29, v29, v211
	v_mul_f32_e32 v30, v30, v212
	v_mul_f32_e32 v31, v31, v213
	v_mul_f32_e32 v32, v32, v214
	v_mul_f32_e32 v33, v33, v215
	s_mov_b32 s9, 0
	s_nop 3
	s_cmp_eq_u32 s10, 0
	s_cbranch_scc1 .Lat_rr_4
	s_cmp_eq_u32 s10, 1
	s_cbranch_scc1 .Lat_rr_8
	s_cmp_eq_u32 s10, 2
	s_cbranch_scc1 .Lat_rr_12
	s_cmp_eq_u32 s10, 3
	s_cbranch_scc1 .Lat_rr_16
	s_cmp_eq_u32 s10, 4
	s_cbranch_scc1 .Lat_rr_20
	s_cmp_eq_u32 s10, 5
	s_cbranch_scc1 .Lat_rr_24
	s_cmp_eq_u32 s10, 6
	s_cbranch_scc1 .Lat_rr_28
	s_cmp_eq_u32 s10, 7
	s_cbranch_scc1 .Lat_rr_31
	s_endpgm
